# v42: v41 + the same late restore barrier (after the unit preamble) in the other four GEMM unit loops
# baseline (speedup 1.0000x reference)
.LBB0_220:
	v_readlane_b32 s28, v254, 12
	v_mov_b32_e32 v167, v1
	v_readlane_b32 s29, v254, 13
	v_mov_b32_e32 v163, v1
	v_readlane_b32 s20, v254, 8
	v_lshl_add_u64 v[8:9], s[28:29], 0, v[166:167]
	v_lshl_add_u64 v[10:11], s[28:29], 0, v[162:163]
	v_mov_b32_e32 v169, v1
	v_readlane_b32 s21, v254, 9
	s_add_i32 m0, s14, 0x18000
	v_lshl_add_u64 v[8:9], v[8:9], 0, s[12:13]
	v_lshl_add_u64 v[12:13], s[20:21], 0, v[168:169]
	v_mov_b32_e32 v165, v1
	s_waitcnt vmcnt(2)
	s_barrier
	global_load_lds_dwordx4 v[8:9], off
	v_lshl_add_u64 v[8:9], v[10:11], 0, s[12:13]
	s_add_i32 m0, s14, 0x1a000
	s_add_i32 s54, s14, 0x8000
	v_lshl_add_u64 v[14:15], s[20:21], 0, v[164:165]
	global_load_lds_dwordx4 v[8:9], off
	v_lshl_add_u64 v[8:9], v[12:13], 0, s[12:13]
	s_mov_b32 m0, s54
	s_add_i32 s55, s14, 0xa000
	v_readlane_b32 s22, v254, 14
	global_load_lds_dwordx4 v[8:9], off
	v_lshl_add_u64 v[8:9], v[14:15], 0, s[12:13]
	s_mov_b32 m0, s55
	v_readlane_b32 s23, v254, 15
	global_load_lds_dwordx4 v[8:9], off
	s_add_i32 m0, s14, 0x1c000
	v_lshl_add_u64 v[8:9], s[22:23], 0, v[166:167]
	global_load_lds_dwordx4 v[8:9], off
	v_lshl_add_u64 v[8:9], s[22:23], 0, v[162:163]
	s_add_i32 m0, s14, 0x1e000
	s_movk_i32 s19, 0x3c0
	global_load_lds_dwordx4 v[8:9], off
	v_and_b32_e32 v8, 48, v3
	v_lshlrev_b32_e32 v9, 6, v3
	v_lshlrev_b32_e32 v3, 2, v3
	s_and_b32 s24, s0, 3
	s_lshl_b32 s33, s18, 6
	s_lshl_b32 s18, s18, 13
	v_and_or_b32 v8, v9, s19, v8
	v_and_b32_e32 v3, 32, v3
	v_bitop3_b32 v9, v8, s18, v3 bitop3:0xde
	s_lshl_b32 s92, s24, 5
	s_lshl_b32 s18, s24, 12
	s_cmpk_lt_u32 s1, 0x100
	s_cselect_b64 s[22:23], -1, 0
	s_cmp_eq_u32 s24, 0
	v_bitop3_b32 v179, v8, s18, v3 bitop3:0xde
	s_cselect_b64 s[18:19], -1, 0
	s_cmp_lt_u32 s24, 2
	s_mov_b32 s1, 0xa000000
	v_cndmask_b32_e64 v3, 0, 1, s[18:19]
	s_cselect_b32 s1, s1, 0x8000000
	s_cmp_gt_u32 s24, 1
	v_readfirstlane_b32 s67, v3
	s_cselect_b64 s[18:19], -1, 0
	v_lshlrev_b32_e32 v3, 16, v6
	v_writelane_b32 v255, s18, 12
	v_and_b32_e32 v3, 0xfffe0000, v3
	v_lshl_add_u32 v3, v5, 13, v3
	v_writelane_b32 v255, s19, 13
	v_readlane_b32 s18, v251, 30
	v_and_b32_e32 v5, 1, v6
	s_add_u32 s1, s18, s1
	v_readlane_b32 s18, v251, 31
	v_lshl_or_b32 v3, v5, 6, v3
	s_addc_u32 s18, s18, 0
	s_lshl_b32 s0, s0, 6
	v_lshl_add_u32 v170, v7, 1, v3
	v_lshlrev_b32_e32 v3, 16, v0
	s_and_b32 s0, s0, 64
	v_and_b32_e32 v3, 0xfffe0000, v3
	s_waitcnt vmcnt(6)
	s_add_u32 s73, s1, s0
	v_lshl_add_u32 v2, v2, 13, v3
	v_and_b32_e32 v0, 1, v0
	v_readlane_b32 s0, v254, 0
	v_lshl_or_b32 v0, v0, 6, v2
	v_readlane_b32 s1, v254, 1
	s_mov_b32 s66, 0
	s_addc_u32 s76, s18, 0
	v_mov_b32_e32 v171, v1
	v_lshl_add_u32 v172, v4, 1, v0
	v_mov_b32_e32 v173, v1
	v_add_u32_e32 v192, 0, v9
	v_readlane_b32 s18, v253, 27
	s_mov_b32 s19, s0
	s_mov_b64 s[0:1], s[20:21]
	v_readlane_b32 s36, v254, 6
	s_barrier
	s_mov_b32 s100, 0
	s_branch .LBB0_223

.LBB0_229:
	s_ashr_i32 s57, s56, 31
	s_lshl_b64 s[30:31], s[56:57], 21
	s_add_u32 s24, s36, s30
	v_readlane_b32 s20, v254, 7
	s_addc_u32 s25, s20, s31
	s_and_b64 s[30:31], s[88:89], exec
	s_cselect_b32 s34, s25, s1
	s_cselect_b32 s35, s24, s0
	s_ashr_i32 s27, s26, 31
	s_lshl_b64 s[30:31], s[26:27], 21
	v_readlane_b32 s20, v254, 2
	s_add_u32 s20, s20, s30
	v_readlane_b32 s21, v254, 3
	s_addc_u32 s21, s21, s31
	s_and_b64 s[30:31], s[88:89], exec
	s_cselect_b32 s27, s21, s29
	s_cselect_b32 s40, s20, s28
	s_add_u32 s0, s0, 0x100080
	s_addc_u32 s1, s1, 0
	s_add_u32 s41, s28, 0x100
	v_mov_b64_e32 v[2:3], 0
	v_mov_b64_e32 v[4:5], 0
	v_mov_b64_e32 v[6:7], 0
	v_mov_b64_e32 v[8:9], 0
	v_mov_b64_e32 v[10:11], 0
	v_mov_b64_e32 v[12:13], 0
	v_mov_b64_e32 v[14:15], 0
	v_mov_b64_e32 v[16:17], 0
	v_mov_b64_e32 v[18:19], 0
	v_mov_b64_e32 v[20:21], 0
	v_mov_b64_e32 v[22:23], 0
	v_mov_b64_e32 v[24:25], 0
	v_mov_b64_e32 v[26:27], 0
	v_mov_b64_e32 v[28:29], 0
	v_mov_b64_e32 v[30:31], 0
	v_mov_b64_e32 v[32:33], 0
	v_mov_b64_e32 v[34:35], 0
	v_mov_b64_e32 v[36:37], 0
	v_mov_b64_e32 v[38:39], 0
	v_mov_b64_e32 v[40:41], 0
	v_mov_b64_e32 v[42:43], 0
	v_mov_b64_e32 v[44:45], 0
	v_mov_b64_e32 v[46:47], 0
	v_mov_b64_e32 v[48:49], 0
	v_mov_b64_e32 v[50:51], 0
	v_mov_b64_e32 v[52:53], 0
	v_mov_b64_e32 v[54:55], 0
	v_mov_b64_e32 v[56:57], 0
	v_mov_b64_e32 v[58:59], 0
	v_mov_b64_e32 v[60:61], 0
	v_mov_b64_e32 v[62:63], 0
	v_mov_b64_e32 v[64:65], 0
	v_mov_b64_e32 v[66:67], 0
	v_mov_b64_e32 v[68:69], 0
	v_mov_b64_e32 v[70:71], 0
	v_mov_b64_e32 v[72:73], 0
	v_mov_b64_e32 v[74:75], 0
	v_mov_b64_e32 v[76:77], 0
	v_mov_b64_e32 v[78:79], 0
	v_mov_b64_e32 v[80:81], 0
	v_mov_b64_e32 v[82:83], 0
	v_mov_b64_e32 v[84:85], 0
	v_mov_b64_e32 v[86:87], 0
	v_mov_b64_e32 v[88:89], 0
	v_mov_b64_e32 v[90:91], 0
	v_mov_b64_e32 v[92:93], 0
	v_mov_b64_e32 v[94:95], 0
	v_mov_b64_e32 v[96:97], 0
	v_mov_b64_e32 v[98:99], 0
	v_mov_b64_e32 v[100:101], 0
	v_mov_b64_e32 v[102:103], 0
	v_mov_b64_e32 v[104:105], 0
	v_mov_b64_e32 v[106:107], 0
	v_mov_b64_e32 v[108:109], 0
	v_mov_b64_e32 v[110:111], 0
	v_mov_b64_e32 v[112:113], 0
	v_mov_b64_e32 v[114:115], 0
	v_mov_b64_e32 v[116:117], 0
	v_mov_b64_e32 v[118:119], 0
	v_mov_b64_e32 v[120:121], 0
	v_mov_b64_e32 v[122:123], 0
	v_mov_b64_e32 v[124:125], 0
	v_mov_b64_e32 v[126:127], 0
	v_mov_b64_e32 v[128:129], 0
	s_addc_u32 s43, s29, 0
	s_mov_b32 s50, -2
	s_cmp_eq_u32 s100, 1
	s_cbranch_scc0 .Lrb_skip_230
	s_barrier
.Lrb_skip_230:
.LBB0_230:
	s_add_u32 s98, s0, 0xfff00000
	s_addc_u32 s99, s1, -1
	s_add_u32 s28, s0, 0xfff00080
	s_addc_u32 s29, s1, -1
	s_add_i32 s51, 0, 0x10000
	s_cmp_eq_u32 s50, 60
	s_cselect_b32 s31, s34, s29
	s_cselect_b32 s30, s35, s28
	v_add_u32_e32 v0, s51, v179
	s_cselect_b32 s29, s27, s43
	s_cselect_b32 s28, s40, s41
	s_add_i32 s77, 0, 0x14000
	ds_read_b128 v[130:133], v0
	ds_read_b128 v[134:137], v0 offset:1024
	ds_read_b128 v[138:141], v0 offset:2048
	ds_read_b128 v[142:145], v0 offset:3072
	v_add_u32_e32 v0, s77, v179
	ds_read_b128 v[146:149], v0
	ds_read_b128 v[150:153], v0 offset:1024
	ds_read_b128 v[154:157], v0 offset:2048
	ds_read_b128 v[158:161], v0 offset:3072
	s_mov_b32 m0, s54
	ds_read_b128 v[174:177], v192
	ds_read_b128 v[180:183], v192 offset:1024
	ds_read_b128 v[184:187], v192 offset:2048
	ds_read_b128 v[188:191], v192 offset:3072
	ds_read_b128 v[200:203], v192 offset:4096
	ds_read_b128 v[204:207], v192 offset:5120
	ds_read_b128 v[208:211], v192 offset:6144
	ds_read_b128 v[212:215], v192 offset:7168
	global_load_lds_dwordx4 v168, s[98:99]
	s_mov_b32 m0, s55
	s_nop 0
	global_load_lds_dwordx4 v164, s[98:99]
	s_add_i32 m0, s14, 0xc000
	s_nop 0
	global_load_lds_dwordx4 v170, s[0:1]
	s_add_i32 m0, s14, 0xe000
	s_nop 0
	global_load_lds_dwordx4 v172, s[0:1]
	s_waitcnt vmcnt(8)
	s_waitcnt lgkmcnt(0)
	s_barrier
	s_waitcnt lgkmcnt(0)
	v_mfma_f32_16x16x32_bf16 v[126:129], v[130:133], v[174:177], v[126:129]
	v_mfma_f32_16x16x32_bf16 v[126:129], v[134:137], v[180:183], v[126:129]
	v_mfma_f32_16x16x32_bf16 v[110:113], v[130:133], v[184:187], v[110:113]
	v_mfma_f32_16x16x32_bf16 v[110:113], v[134:137], v[188:191], v[110:113]
	v_mfma_f32_16x16x32_bf16 v[94:97], v[130:133], v[200:203], v[94:97]
	v_mfma_f32_16x16x32_bf16 v[94:97], v[134:137], v[204:207], v[94:97]
	v_mfma_f32_16x16x32_bf16 v[78:81], v[130:133], v[208:211], v[78:81]
	v_mfma_f32_16x16x32_bf16 v[78:81], v[134:137], v[212:215], v[78:81]
	v_mfma_f32_16x16x32_bf16 v[122:125], v[138:141], v[174:177], v[122:125]
	v_mfma_f32_16x16x32_bf16 v[122:125], v[142:145], v[180:183], v[122:125]
	v_mfma_f32_16x16x32_bf16 v[106:109], v[138:141], v[184:187], v[106:109]
	v_mfma_f32_16x16x32_bf16 v[106:109], v[142:145], v[188:191], v[106:109]
	v_mfma_f32_16x16x32_bf16 v[90:93], v[138:141], v[200:203], v[90:93]
	v_mfma_f32_16x16x32_bf16 v[90:93], v[142:145], v[204:207], v[90:93]
	v_mfma_f32_16x16x32_bf16 v[74:77], v[138:141], v[208:211], v[74:77]
	v_mfma_f32_16x16x32_bf16 v[74:77], v[142:145], v[212:215], v[74:77]
	v_mfma_f32_16x16x32_bf16 v[118:121], v[146:149], v[174:177], v[118:121]
	v_mfma_f32_16x16x32_bf16 v[118:121], v[150:153], v[180:183], v[118:121]
	v_mfma_f32_16x16x32_bf16 v[102:105], v[146:149], v[184:187], v[102:105]
	v_mfma_f32_16x16x32_bf16 v[102:105], v[150:153], v[188:191], v[102:105]
	v_mfma_f32_16x16x32_bf16 v[86:89], v[146:149], v[200:203], v[86:89]
	v_mfma_f32_16x16x32_bf16 v[86:89], v[150:153], v[204:207], v[86:89]
	v_mfma_f32_16x16x32_bf16 v[70:73], v[146:149], v[208:211], v[70:73]
	v_mfma_f32_16x16x32_bf16 v[70:73], v[150:153], v[212:215], v[70:73]
	v_mfma_f32_16x16x32_bf16 v[114:117], v[154:157], v[174:177], v[114:117]
	v_mfma_f32_16x16x32_bf16 v[114:117], v[158:161], v[180:183], v[114:117]
	v_mfma_f32_16x16x32_bf16 v[98:101], v[154:157], v[184:187], v[98:101]
	v_mfma_f32_16x16x32_bf16 v[98:101], v[158:161], v[188:191], v[98:101]
	v_mfma_f32_16x16x32_bf16 v[82:85], v[154:157], v[200:203], v[82:85]
	v_mfma_f32_16x16x32_bf16 v[82:85], v[158:161], v[204:207], v[82:85]
	v_mfma_f32_16x16x32_bf16 v[66:69], v[154:157], v[208:211], v[66:69]
	v_mfma_f32_16x16x32_bf16 v[66:69], v[158:161], v[212:215], v[66:69]
	s_barrier
	s_add_i32 s51, s51, s9
	s_mov_b32 m0, s51
	ds_read_b128 v[174:177], v192 offset:16384
	ds_read_b128 v[180:183], v192 offset:17408
	ds_read_b128 v[184:187], v192 offset:18432
	ds_read_b128 v[188:191], v192 offset:19456
	ds_read_b128 v[200:203], v192 offset:20480
	ds_read_b128 v[204:207], v192 offset:21504
	ds_read_b128 v[208:211], v192 offset:22528
	ds_read_b128 v[212:215], v192 offset:23552
	global_load_lds_dwordx4 v166, s[28:29]
	s_add_i32 m0, s51, 0x2000
	s_add_u32 s80, s28, 0x100000
	s_addc_u32 s81, s29, 0
	s_add_i32 s51, s77, s9
	global_load_lds_dwordx4 v162, s[28:29]
	s_mov_b32 m0, s51
	s_nop 0
	global_load_lds_dwordx4 v166, s[80:81]
	s_add_i32 m0, s51, 0x2000
	s_nop 0
	global_load_lds_dwordx4 v162, s[80:81]
	s_waitcnt vmcnt(6)
	s_waitcnt lgkmcnt(0)
	s_barrier
	s_waitcnt lgkmcnt(0)
	v_mfma_f32_16x16x32_bf16 v[62:65], v[130:133], v[174:177], v[62:65]
	v_mfma_f32_16x16x32_bf16 v[62:65], v[134:137], v[180:183], v[62:65]
	v_mfma_f32_16x16x32_bf16 v[46:49], v[130:133], v[184:187], v[46:49]
	v_mfma_f32_16x16x32_bf16 v[46:49], v[134:137], v[188:191], v[46:49]
	v_mfma_f32_16x16x32_bf16 v[30:33], v[130:133], v[200:203], v[30:33]
	v_mfma_f32_16x16x32_bf16 v[30:33], v[134:137], v[204:207], v[30:33]
	v_mfma_f32_16x16x32_bf16 v[14:17], v[130:133], v[208:211], v[14:17]
	v_mfma_f32_16x16x32_bf16 v[14:17], v[134:137], v[212:215], v[14:17]
	v_mfma_f32_16x16x32_bf16 v[58:61], v[138:141], v[174:177], v[58:61]
	v_mfma_f32_16x16x32_bf16 v[58:61], v[142:145], v[180:183], v[58:61]
	v_mfma_f32_16x16x32_bf16 v[42:45], v[138:141], v[184:187], v[42:45]
	v_mfma_f32_16x16x32_bf16 v[42:45], v[142:145], v[188:191], v[42:45]
	v_mfma_f32_16x16x32_bf16 v[26:29], v[138:141], v[200:203], v[26:29]
	v_mfma_f32_16x16x32_bf16 v[26:29], v[142:145], v[204:207], v[26:29]
	v_mfma_f32_16x16x32_bf16 v[10:13], v[138:141], v[208:211], v[10:13]
	v_mfma_f32_16x16x32_bf16 v[10:13], v[142:145], v[212:215], v[10:13]
	v_mfma_f32_16x16x32_bf16 v[54:57], v[146:149], v[174:177], v[54:57]
	v_mfma_f32_16x16x32_bf16 v[54:57], v[150:153], v[180:183], v[54:57]
	v_mfma_f32_16x16x32_bf16 v[38:41], v[146:149], v[184:187], v[38:41]
	v_mfma_f32_16x16x32_bf16 v[38:41], v[150:153], v[188:191], v[38:41]
	v_mfma_f32_16x16x32_bf16 v[22:25], v[146:149], v[200:203], v[22:25]
	v_mfma_f32_16x16x32_bf16 v[22:25], v[150:153], v[204:207], v[22:25]
	v_mfma_f32_16x16x32_bf16 v[6:9], v[146:149], v[208:211], v[6:9]
	v_mfma_f32_16x16x32_bf16 v[6:9], v[150:153], v[212:215], v[6:9]
	v_mfma_f32_16x16x32_bf16 v[50:53], v[154:157], v[174:177], v[50:53]
	v_mfma_f32_16x16x32_bf16 v[50:53], v[158:161], v[180:183], v[50:53]
	v_mfma_f32_16x16x32_bf16 v[34:37], v[154:157], v[184:187], v[34:37]
	v_mfma_f32_16x16x32_bf16 v[34:37], v[158:161], v[188:191], v[34:37]
	v_mfma_f32_16x16x32_bf16 v[18:21], v[154:157], v[200:203], v[18:21]
	v_mfma_f32_16x16x32_bf16 v[18:21], v[158:161], v[204:207], v[18:21]
	v_mfma_f32_16x16x32_bf16 v[2:5], v[154:157], v[208:211], v[2:5]
	v_mfma_f32_16x16x32_bf16 v[2:5], v[158:161], v[212:215], v[2:5]
	s_barrier
	s_add_i32 s51, 0, 0x18000
	v_add_u32_e32 v0, s51, v179
	s_add_i32 s77, 0, 0x1c000
	ds_read_b128 v[130:133], v0
	ds_read_b128 v[134:137], v0 offset:1024
	ds_read_b128 v[138:141], v0 offset:2048
	ds_read_b128 v[142:145], v0 offset:3072
	v_add_u32_e32 v0, s77, v179
	ds_read_b128 v[146:149], v0
	ds_read_b128 v[150:153], v0 offset:1024
	ds_read_b128 v[154:157], v0 offset:2048
	ds_read_b128 v[158:161], v0 offset:3072
	s_mov_b32 m0, s14
	ds_read_b128 v[174:177], v192 offset:32768
	ds_read_b128 v[180:183], v192 offset:33792
	ds_read_b128 v[184:187], v192 offset:34816
	ds_read_b128 v[188:191], v192 offset:35840
	ds_read_b128 v[200:203], v192 offset:36864
	ds_read_b128 v[204:207], v192 offset:37888
	ds_read_b128 v[208:211], v192 offset:38912
	ds_read_b128 v[212:215], v192 offset:39936
	global_load_lds_dwordx4 v168, s[30:31]
	s_mov_b32 m0, s15
	s_nop 0
	global_load_lds_dwordx4 v164, s[30:31]
	s_add_u32 s30, s30, 0x100000
	s_addc_u32 s31, s31, 0
	s_mov_b32 m0, s52
	s_nop 0
	global_load_lds_dwordx4 v168, s[30:31]
	s_mov_b32 m0, s53
	s_nop 0
	global_load_lds_dwordx4 v164, s[30:31]
	s_waitcnt vmcnt(8)
	s_waitcnt lgkmcnt(0)
	s_barrier
	s_waitcnt lgkmcnt(0)
	v_mfma_f32_16x16x32_bf16 v[126:129], v[130:133], v[174:177], v[126:129]
	v_mfma_f32_16x16x32_bf16 v[126:129], v[134:137], v[180:183], v[126:129]
	v_mfma_f32_16x16x32_bf16 v[110:113], v[130:133], v[184:187], v[110:113]
	v_mfma_f32_16x16x32_bf16 v[110:113], v[134:137], v[188:191], v[110:113]
	v_mfma_f32_16x16x32_bf16 v[94:97], v[130:133], v[200:203], v[94:97]
	v_mfma_f32_16x16x32_bf16 v[94:97], v[134:137], v[204:207], v[94:97]
	v_mfma_f32_16x16x32_bf16 v[78:81], v[130:133], v[208:211], v[78:81]
	v_mfma_f32_16x16x32_bf16 v[78:81], v[134:137], v[212:215], v[78:81]
	v_mfma_f32_16x16x32_bf16 v[122:125], v[138:141], v[174:177], v[122:125]
	v_mfma_f32_16x16x32_bf16 v[122:125], v[142:145], v[180:183], v[122:125]
	v_mfma_f32_16x16x32_bf16 v[106:109], v[138:141], v[184:187], v[106:109]
	v_mfma_f32_16x16x32_bf16 v[106:109], v[142:145], v[188:191], v[106:109]
	v_mfma_f32_16x16x32_bf16 v[90:93], v[138:141], v[200:203], v[90:93]
	v_mfma_f32_16x16x32_bf16 v[90:93], v[142:145], v[204:207], v[90:93]
	v_mfma_f32_16x16x32_bf16 v[74:77], v[138:141], v[208:211], v[74:77]
	v_mfma_f32_16x16x32_bf16 v[74:77], v[142:145], v[212:215], v[74:77]
	v_mfma_f32_16x16x32_bf16 v[118:121], v[146:149], v[174:177], v[118:121]
	v_mfma_f32_16x16x32_bf16 v[118:121], v[150:153], v[180:183], v[118:121]
	v_mfma_f32_16x16x32_bf16 v[102:105], v[146:149], v[184:187], v[102:105]
	v_mfma_f32_16x16x32_bf16 v[102:105], v[150:153], v[188:191], v[102:105]
	v_mfma_f32_16x16x32_bf16 v[86:89], v[146:149], v[200:203], v[86:89]
	v_mfma_f32_16x16x32_bf16 v[86:89], v[150:153], v[204:207], v[86:89]
	v_mfma_f32_16x16x32_bf16 v[70:73], v[146:149], v[208:211], v[70:73]
	v_mfma_f32_16x16x32_bf16 v[70:73], v[150:153], v[212:215], v[70:73]
	v_mfma_f32_16x16x32_bf16 v[114:117], v[154:157], v[174:177], v[114:117]
	v_mfma_f32_16x16x32_bf16 v[114:117], v[158:161], v[180:183], v[114:117]
	v_mfma_f32_16x16x32_bf16 v[98:101], v[154:157], v[184:187], v[98:101]
	v_mfma_f32_16x16x32_bf16 v[98:101], v[158:161], v[188:191], v[98:101]
	v_mfma_f32_16x16x32_bf16 v[82:85], v[154:157], v[200:203], v[82:85]
	v_mfma_f32_16x16x32_bf16 v[82:85], v[158:161], v[204:207], v[82:85]
	v_mfma_f32_16x16x32_bf16 v[66:69], v[154:157], v[208:211], v[66:69]
	v_mfma_f32_16x16x32_bf16 v[66:69], v[158:161], v[212:215], v[66:69]
	s_barrier
	s_add_u32 s98, s28, 0x80
	s_addc_u32 s99, s29, 0
	s_add_i32 s30, s51, s9
	s_mov_b32 m0, s30
	ds_read_b128 v[174:177], v192 offset:49152
	ds_read_b128 v[180:183], v192 offset:50176
	ds_read_b128 v[184:187], v192 offset:51200
	ds_read_b128 v[188:191], v192 offset:52224
	ds_read_b128 v[200:203], v192 offset:53248
	ds_read_b128 v[204:207], v192 offset:54272
	ds_read_b128 v[208:211], v192 offset:55296
	ds_read_b128 v[212:215], v192 offset:56320
	global_load_lds_dwordx4 v166, s[98:99]
	s_add_i32 m0, s30, 0x2000
	s_add_u32 s28, s28, 0x100080
	s_addc_u32 s29, s29, 0
	s_add_i32 s30, s77, s9
	global_load_lds_dwordx4 v162, s[98:99]
	s_mov_b32 m0, s30
	s_nop 0
	global_load_lds_dwordx4 v166, s[28:29]
	s_add_i32 m0, s30, 0x2000
	s_nop 0
	global_load_lds_dwordx4 v162, s[28:29]
	s_waitcnt vmcnt(6)
	s_waitcnt lgkmcnt(0)
	s_barrier
	s_waitcnt lgkmcnt(0)
	v_mfma_f32_16x16x32_bf16 v[62:65], v[130:133], v[174:177], v[62:65]
	v_mfma_f32_16x16x32_bf16 v[62:65], v[134:137], v[180:183], v[62:65]
	v_mfma_f32_16x16x32_bf16 v[46:49], v[130:133], v[184:187], v[46:49]
	v_mfma_f32_16x16x32_bf16 v[46:49], v[134:137], v[188:191], v[46:49]
	v_mfma_f32_16x16x32_bf16 v[30:33], v[130:133], v[200:203], v[30:33]
	v_mfma_f32_16x16x32_bf16 v[30:33], v[134:137], v[204:207], v[30:33]
	v_mfma_f32_16x16x32_bf16 v[14:17], v[130:133], v[208:211], v[14:17]
	v_mfma_f32_16x16x32_bf16 v[14:17], v[134:137], v[212:215], v[14:17]
	v_mfma_f32_16x16x32_bf16 v[58:61], v[138:141], v[174:177], v[58:61]
	v_mfma_f32_16x16x32_bf16 v[58:61], v[142:145], v[180:183], v[58:61]
	v_mfma_f32_16x16x32_bf16 v[42:45], v[138:141], v[184:187], v[42:45]
	v_mfma_f32_16x16x32_bf16 v[42:45], v[142:145], v[188:191], v[42:45]
	v_mfma_f32_16x16x32_bf16 v[26:29], v[138:141], v[200:203], v[26:29]
	v_mfma_f32_16x16x32_bf16 v[26:29], v[142:145], v[204:207], v[26:29]
	v_mfma_f32_16x16x32_bf16 v[10:13], v[138:141], v[208:211], v[10:13]
	v_mfma_f32_16x16x32_bf16 v[10:13], v[142:145], v[212:215], v[10:13]
	v_mfma_f32_16x16x32_bf16 v[54:57], v[146:149], v[174:177], v[54:57]
	v_mfma_f32_16x16x32_bf16 v[54:57], v[150:153], v[180:183], v[54:57]
	v_mfma_f32_16x16x32_bf16 v[38:41], v[146:149], v[184:187], v[38:41]
	v_mfma_f32_16x16x32_bf16 v[38:41], v[150:153], v[188:191], v[38:41]
	v_mfma_f32_16x16x32_bf16 v[22:25], v[146:149], v[200:203], v[22:25]
	v_mfma_f32_16x16x32_bf16 v[22:25], v[150:153], v[204:207], v[22:25]
	v_mfma_f32_16x16x32_bf16 v[6:9], v[146:149], v[208:211], v[6:9]
	v_mfma_f32_16x16x32_bf16 v[6:9], v[150:153], v[212:215], v[6:9]
	v_mfma_f32_16x16x32_bf16 v[50:53], v[154:157], v[174:177], v[50:53]
	v_mfma_f32_16x16x32_bf16 v[50:53], v[158:161], v[180:183], v[50:53]
	v_mfma_f32_16x16x32_bf16 v[34:37], v[154:157], v[184:187], v[34:37]
	v_mfma_f32_16x16x32_bf16 v[34:37], v[158:161], v[188:191], v[34:37]
	v_mfma_f32_16x16x32_bf16 v[18:21], v[154:157], v[200:203], v[18:21]
	v_mfma_f32_16x16x32_bf16 v[18:21], v[158:161], v[204:207], v[18:21]
	v_mfma_f32_16x16x32_bf16 v[2:5], v[154:157], v[208:211], v[2:5]
	v_mfma_f32_16x16x32_bf16 v[2:5], v[158:161], v[212:215], v[2:5]
	s_barrier
	s_add_i32 s50, s50, 2
	s_add_u32 s0, s0, 0x100
	s_addc_u32 s1, s1, 0
	s_add_u32 s41, s41, 0x100
	s_addc_u32 s43, s43, 0
	s_cmp_gt_u32 s50, 61
	s_cbranch_scc0 .LBB0_230
	s_and_b64 vcc, exec, s[22:23]
	s_cbranch_vccz .LBB0_233
	s_barrier

.LBB0_285:
	s_mov_b32 s100, 0
	s_andn2_b64 vcc, exec, s[38:39]
	s_cbranch_vccnz .LBB0_221
	s_mov_b32 s100, 1
	s_branch .LBB0_221

.LBB0_567:
	v_mov_b32_e32 v205, v1
	v_lshl_add_u64 v[8:9], s[34:35], 0, v[204:205]
	v_mov_b32_e32 v201, v1
	v_readlane_b32 s30, v253, 29
	s_lshl_b32 s20, s20, 5
	v_lshl_add_u64 v[10:11], s[34:35], 0, v[200:201]
	v_mov_b32_e32 v207, v1
	v_readlane_b32 s31, v253, 30
	s_and_b32 s23, s20, 0x60
	s_add_i32 m0, s46, 0x18000
	v_lshl_add_u64 v[8:9], v[8:9], 0, s[12:13]
	v_lshl_add_u64 v[12:13], s[30:31], 0, v[206:207]
	v_mov_b32_e32 v203, v1
	s_lshl_b32 s22, s19, 13
	s_lshl_b32 s24, s23, 7
	s_waitcnt vmcnt(2)
	s_barrier
	global_load_lds_dwordx4 v[8:9], off
	v_lshl_add_u64 v[8:9], v[10:11], 0, s[12:13]
	s_add_i32 m0, s46, 0x1a000
	s_add_i32 s50, s46, 0x8000
	s_add_i32 s51, s46, 0xa000
	v_lshl_add_u64 v[14:15], s[30:31], 0, v[202:203]
	global_load_lds_dwordx4 v[8:9], off
	v_lshl_add_u64 v[8:9], v[12:13], 0, s[12:13]
	s_mov_b32 m0, s50
	s_add_u32 s20, s34, 0x80080
	global_load_lds_dwordx4 v[8:9], off
	v_lshl_add_u64 v[8:9], v[14:15], 0, s[12:13]
	s_mov_b32 m0, s51
	s_addc_u32 s21, s35, 0
	global_load_lds_dwordx4 v[8:9], off
	s_add_i32 m0, s46, 0x1c000
	v_lshl_add_u64 v[8:9], s[20:21], 0, v[204:205]
	global_load_lds_dwordx4 v[8:9], off
	v_lshl_add_u64 v[8:9], s[20:21], 0, v[200:201]
	s_add_i32 m0, s46, 0x1e000
	s_cmpk_lt_u32 s18, 0x100
	global_load_lds_dwordx4 v[8:9], off
	v_lshrrev_b32_e32 v9, 1, v0
	v_and_b32_e32 v9, 24, v9
	v_and_b32_e32 v8, 15, v0
	v_lshlrev_b32_e32 v10, 1, v9
	v_lshlrev_b32_e32 v0, 2, v0
	v_lshl_or_b32 v199, s19, 6, v8
	v_lshl_or_b32 v8, v8, 6, v10
	v_and_b32_e32 v0, 32, v0
	v_bitop3_b32 v10, v8, s22, v0 bitop3:0xde
	v_bitop3_b32 v228, v8, s24, v0 bitop3:0xde
	v_lshlrev_b32_e32 v0, 15, v6
	v_and_b32_e32 v0, 0xffff0000, v0
	v_lshl_add_u32 v0, v5, 12, v0
	v_and_b32_e32 v5, 1, v6
	v_lshl_or_b32 v0, v5, 6, v0
	v_lshl_add_u32 v208, v7, 1, v0
	v_lshlrev_b32_e32 v0, 15, v2
	v_and_b32_e32 v0, 0xffff0000, v0
	v_lshl_add_u32 v0, v3, 12, v0
	v_and_b32_e32 v2, 1, v2
	s_waitcnt vmcnt(6)
	v_lshl_or_b32 v0, v2, 6, v0
	v_mov_b32_e32 v2, v1
	v_mov_b32_e32 v3, v1
	v_or_b32_e32 v229, s23, v9
	v_lshl_add_u32 v210, v4, 1, v0
	v_mov_b32_e32 v0, v1
	v_add_u32_e32 v230, 0, v10
	v_mov_b64_e32 v[6:7], v[2:3]
	v_mov_b64_e32 v[10:11], v[2:3]
	v_mov_b64_e32 v[14:15], v[2:3]
	v_mov_b64_e32 v[18:19], v[2:3]
	v_mov_b64_e32 v[22:23], v[2:3]
	v_mov_b64_e32 v[26:27], v[2:3]
	v_mov_b64_e32 v[30:31], v[2:3]
	v_mov_b64_e32 v[34:35], v[2:3]
	v_mov_b64_e32 v[38:39], v[2:3]
	v_mov_b64_e32 v[42:43], v[2:3]
	v_mov_b64_e32 v[46:47], v[2:3]
	v_mov_b64_e32 v[50:51], v[2:3]
	v_mov_b64_e32 v[54:55], v[2:3]
	v_mov_b64_e32 v[58:59], v[2:3]
	v_mov_b64_e32 v[62:63], v[2:3]
	v_mov_b64_e32 v[66:67], v[2:3]
	v_mov_b64_e32 v[70:71], v[2:3]
	v_mov_b64_e32 v[74:75], v[2:3]
	v_mov_b64_e32 v[78:79], v[2:3]
	v_mov_b64_e32 v[82:83], v[2:3]
	v_mov_b64_e32 v[86:87], v[2:3]
	v_mov_b64_e32 v[90:91], v[2:3]
	v_mov_b64_e32 v[94:95], v[2:3]
	v_mov_b64_e32 v[98:99], v[2:3]
	v_mov_b64_e32 v[102:103], v[2:3]
	v_mov_b64_e32 v[106:107], v[2:3]
	v_mov_b64_e32 v[110:111], v[2:3]
	v_mov_b64_e32 v[114:115], v[2:3]
	v_mov_b64_e32 v[118:119], v[2:3]
	v_mov_b64_e32 v[122:123], v[2:3]
	v_mov_b64_e32 v[126:127], v[2:3]
	v_mov_b64_e32 v[130:131], v[2:3]
	v_readlane_b32 s22, v253, 50
	s_cselect_b64 s[20:21], -1, 0
	v_mov_b32_e32 v209, v1
	v_mov_b32_e32 v211, v1
	s_mov_b32 s52, 0
	v_mov_b64_e32 v[4:5], v[0:1]
	v_mov_b64_e32 v[8:9], v[0:1]
	v_mov_b64_e32 v[12:13], v[0:1]
	v_mov_b64_e32 v[16:17], v[0:1]
	v_mov_b64_e32 v[20:21], v[0:1]
	v_mov_b64_e32 v[24:25], v[0:1]
	v_mov_b64_e32 v[28:29], v[0:1]
	v_mov_b64_e32 v[32:33], v[0:1]
	v_mov_b64_e32 v[36:37], v[0:1]
	v_mov_b64_e32 v[40:41], v[0:1]
	v_mov_b64_e32 v[44:45], v[0:1]
	v_mov_b64_e32 v[48:49], v[0:1]
	v_mov_b64_e32 v[52:53], v[0:1]
	v_mov_b64_e32 v[56:57], v[0:1]
	v_mov_b64_e32 v[60:61], v[0:1]
	v_mov_b64_e32 v[64:65], v[0:1]
	v_mov_b64_e32 v[68:69], v[0:1]
	v_mov_b64_e32 v[72:73], v[0:1]
	v_mov_b64_e32 v[76:77], v[0:1]
	v_mov_b64_e32 v[80:81], v[0:1]
	v_mov_b64_e32 v[84:85], v[0:1]
	v_mov_b64_e32 v[88:89], v[0:1]
	v_mov_b64_e32 v[92:93], v[0:1]
	v_mov_b64_e32 v[96:97], v[0:1]
	v_mov_b64_e32 v[100:101], v[0:1]
	v_mov_b64_e32 v[104:105], v[0:1]
	v_mov_b64_e32 v[108:109], v[0:1]
	v_mov_b64_e32 v[112:113], v[0:1]
	v_mov_b64_e32 v[116:117], v[0:1]
	v_mov_b64_e32 v[120:121], v[0:1]
	v_mov_b64_e32 v[124:125], v[0:1]
	v_mov_b64_e32 v[128:129], v[0:1]
	v_readlane_b32 s18, v253, 28
	s_mov_b32 s53, s22
	s_barrier
	v_readlane_b32 s23, v253, 51
	s_mov_b32 s100, 0
	s_branch .LBB0_570

.LBB0_576:
	s_ashr_i32 s23, s22, 31
	s_lshl_b64 s[26:27], s[22:23], 20
	s_add_u32 s26, s68, s26
	s_addc_u32 s27, s69, s27
	s_and_b64 s[28:29], s[40:41], exec
	s_cselect_b32 s19, s27, s31
	s_cselect_b32 s23, s26, s30
	s_ashr_i32 s25, s24, 31
	s_lshl_b64 s[28:29], s[24:25], 20
	s_add_u32 s28, s9, s28
	s_addc_u32 s29, s14, s29
	s_and_b64 s[42:43], s[40:41], exec
	s_cselect_b32 s25, s29, s35
	s_cselect_b32 s54, s28, s34
	s_add_u32 s30, s30, 0x80080
	s_addc_u32 s31, s31, 0
	s_add_u32 s55, s34, 0x100
	s_addc_u32 s56, s35, 0
	s_mov_b32 s57, -2
	s_cmp_eq_u32 s100, 1
	s_cbranch_scc0 .Lrb_skip_577
	s_barrier
.Lrb_skip_577:
.LBB0_577:
	s_add_u32 s98, s30, 0xfff80000
	s_addc_u32 s99, s31, -1
	s_add_u32 s34, s30, 0xfff80080
	s_addc_u32 s35, s31, -1
	s_add_i32 s66, 0, 0x10000
	s_cmp_eq_u32 s57, 28
	s_cselect_b32 s43, s19, s35
	s_cselect_b32 s42, s23, s34
	v_add_u32_e32 v0, s66, v228
	s_cselect_b32 s35, s25, s56
	s_cselect_b32 s34, s54, s55
	s_add_i32 s73, 0, 0x14000
	ds_read_b128 v[132:135], v0
	ds_read_b128 v[136:139], v0 offset:1024
	ds_read_b128 v[140:143], v0 offset:2048
	ds_read_b128 v[144:147], v0 offset:3072
	v_add_u32_e32 v0, s73, v228
	ds_read_b128 v[148:151], v0
	ds_read_b128 v[152:155], v0 offset:1024
	ds_read_b128 v[156:159], v0 offset:2048
	ds_read_b128 v[160:163], v0 offset:3072
	s_mov_b32 m0, s50
	ds_read_b128 v[164:167], v230
	ds_read_b128 v[168:171], v230 offset:1024
	ds_read_b128 v[172:175], v230 offset:2048
	ds_read_b128 v[176:179], v230 offset:3072
	ds_read_b128 v[180:183], v230 offset:4096
	ds_read_b128 v[184:187], v230 offset:5120
	ds_read_b128 v[188:191], v230 offset:6144
	ds_read_b128 v[192:195], v230 offset:7168
	global_load_lds_dwordx4 v206, s[98:99]
	s_mov_b32 m0, s51
	s_nop 0
	global_load_lds_dwordx4 v202, s[98:99]
	s_add_i32 m0, s46, 0xc000
	s_nop 0
	global_load_lds_dwordx4 v208, s[30:31]
	s_add_i32 m0, s46, 0xe000
	s_nop 0
	global_load_lds_dwordx4 v210, s[30:31]
	s_waitcnt vmcnt(8)
	s_waitcnt lgkmcnt(0)
	s_barrier
	s_waitcnt lgkmcnt(0)
	v_mfma_f32_16x16x32_bf16 v[128:131], v[132:135], v[164:167], v[128:131]
	v_mfma_f32_16x16x32_bf16 v[128:131], v[136:139], v[168:171], v[128:131]
	v_mfma_f32_16x16x32_bf16 v[120:123], v[132:135], v[172:175], v[120:123]
	v_mfma_f32_16x16x32_bf16 v[120:123], v[136:139], v[176:179], v[120:123]
	v_mfma_f32_16x16x32_bf16 v[112:115], v[132:135], v[180:183], v[112:115]
	v_mfma_f32_16x16x32_bf16 v[112:115], v[136:139], v[184:187], v[112:115]
	v_mfma_f32_16x16x32_bf16 v[104:107], v[132:135], v[188:191], v[104:107]
	v_mfma_f32_16x16x32_bf16 v[104:107], v[136:139], v[192:195], v[104:107]
	v_mfma_f32_16x16x32_bf16 v[124:127], v[140:143], v[164:167], v[124:127]
	v_mfma_f32_16x16x32_bf16 v[124:127], v[144:147], v[168:171], v[124:127]
	v_mfma_f32_16x16x32_bf16 v[116:119], v[140:143], v[172:175], v[116:119]
	v_mfma_f32_16x16x32_bf16 v[116:119], v[144:147], v[176:179], v[116:119]
	v_mfma_f32_16x16x32_bf16 v[108:111], v[140:143], v[180:183], v[108:111]
	v_mfma_f32_16x16x32_bf16 v[108:111], v[144:147], v[184:187], v[108:111]
	v_mfma_f32_16x16x32_bf16 v[100:103], v[140:143], v[188:191], v[100:103]
	v_mfma_f32_16x16x32_bf16 v[100:103], v[144:147], v[192:195], v[100:103]
	v_mfma_f32_16x16x32_bf16 v[96:99], v[148:151], v[164:167], v[96:99]
	v_mfma_f32_16x16x32_bf16 v[96:99], v[152:155], v[168:171], v[96:99]
	v_mfma_f32_16x16x32_bf16 v[88:91], v[148:151], v[172:175], v[88:91]
	v_mfma_f32_16x16x32_bf16 v[88:91], v[152:155], v[176:179], v[88:91]
	v_mfma_f32_16x16x32_bf16 v[80:83], v[148:151], v[180:183], v[80:83]
	v_mfma_f32_16x16x32_bf16 v[80:83], v[152:155], v[184:187], v[80:83]
	v_mfma_f32_16x16x32_bf16 v[72:75], v[148:151], v[188:191], v[72:75]
	v_mfma_f32_16x16x32_bf16 v[72:75], v[152:155], v[192:195], v[72:75]
	v_mfma_f32_16x16x32_bf16 v[92:95], v[156:159], v[164:167], v[92:95]
	v_mfma_f32_16x16x32_bf16 v[92:95], v[160:163], v[168:171], v[92:95]
	v_mfma_f32_16x16x32_bf16 v[84:87], v[156:159], v[172:175], v[84:87]
	v_mfma_f32_16x16x32_bf16 v[84:87], v[160:163], v[176:179], v[84:87]
	v_mfma_f32_16x16x32_bf16 v[76:79], v[156:159], v[180:183], v[76:79]
	v_mfma_f32_16x16x32_bf16 v[76:79], v[160:163], v[184:187], v[76:79]
	v_mfma_f32_16x16x32_bf16 v[68:71], v[156:159], v[188:191], v[68:71]
	v_mfma_f32_16x16x32_bf16 v[68:71], v[160:163], v[192:195], v[68:71]
	s_barrier
	s_add_i32 s66, s66, s15
	s_mov_b32 m0, s66
	ds_read_b128 v[164:167], v230 offset:16384
	ds_read_b128 v[168:171], v230 offset:17408
	ds_read_b128 v[172:175], v230 offset:18432
	ds_read_b128 v[176:179], v230 offset:19456
	ds_read_b128 v[180:183], v230 offset:20480
	ds_read_b128 v[184:187], v230 offset:21504
	ds_read_b128 v[188:191], v230 offset:22528
	ds_read_b128 v[192:195], v230 offset:23552
	global_load_lds_dwordx4 v204, s[34:35]
	s_add_i32 m0, s66, 0x2000
	s_add_u32 s66, s34, 0x80000
	s_addc_u32 s67, s35, 0
	s_add_i32 s73, s73, s15
	global_load_lds_dwordx4 v200, s[34:35]
	s_mov_b32 m0, s73
	s_nop 0
	global_load_lds_dwordx4 v204, s[66:67]
	s_add_i32 m0, s73, 0x2000
	s_nop 0
	global_load_lds_dwordx4 v200, s[66:67]
	s_waitcnt vmcnt(6)
	s_waitcnt lgkmcnt(0)
	s_barrier
	s_waitcnt lgkmcnt(0)
	v_mfma_f32_16x16x32_bf16 v[64:67], v[132:135], v[164:167], v[64:67]
	v_mfma_f32_16x16x32_bf16 v[64:67], v[136:139], v[168:171], v[64:67]
	v_mfma_f32_16x16x32_bf16 v[56:59], v[132:135], v[172:175], v[56:59]
	v_mfma_f32_16x16x32_bf16 v[56:59], v[136:139], v[176:179], v[56:59]
	v_mfma_f32_16x16x32_bf16 v[48:51], v[132:135], v[180:183], v[48:51]
	v_mfma_f32_16x16x32_bf16 v[48:51], v[136:139], v[184:187], v[48:51]
	v_mfma_f32_16x16x32_bf16 v[40:43], v[132:135], v[188:191], v[40:43]
	v_mfma_f32_16x16x32_bf16 v[40:43], v[136:139], v[192:195], v[40:43]
	v_mfma_f32_16x16x32_bf16 v[60:63], v[140:143], v[164:167], v[60:63]
	v_mfma_f32_16x16x32_bf16 v[60:63], v[144:147], v[168:171], v[60:63]
	v_mfma_f32_16x16x32_bf16 v[52:55], v[140:143], v[172:175], v[52:55]
	v_mfma_f32_16x16x32_bf16 v[52:55], v[144:147], v[176:179], v[52:55]
	v_mfma_f32_16x16x32_bf16 v[44:47], v[140:143], v[180:183], v[44:47]
	v_mfma_f32_16x16x32_bf16 v[44:47], v[144:147], v[184:187], v[44:47]
	v_mfma_f32_16x16x32_bf16 v[36:39], v[140:143], v[188:191], v[36:39]
	v_mfma_f32_16x16x32_bf16 v[36:39], v[144:147], v[192:195], v[36:39]
	v_mfma_f32_16x16x32_bf16 v[32:35], v[148:151], v[164:167], v[32:35]
	v_mfma_f32_16x16x32_bf16 v[32:35], v[152:155], v[168:171], v[32:35]
	v_mfma_f32_16x16x32_bf16 v[28:31], v[156:159], v[164:167], v[28:31]
	v_mfma_f32_16x16x32_bf16 v[28:31], v[160:163], v[168:171], v[28:31]
	v_mfma_f32_16x16x32_bf16 v[24:27], v[148:151], v[172:175], v[24:27]
	v_mfma_f32_16x16x32_bf16 v[24:27], v[152:155], v[176:179], v[24:27]
	v_mfma_f32_16x16x32_bf16 v[20:23], v[156:159], v[172:175], v[20:23]
	v_mfma_f32_16x16x32_bf16 v[20:23], v[160:163], v[176:179], v[20:23]
	v_mfma_f32_16x16x32_bf16 v[16:19], v[148:151], v[180:183], v[16:19]
	v_mfma_f32_16x16x32_bf16 v[16:19], v[152:155], v[184:187], v[16:19]
	v_mfma_f32_16x16x32_bf16 v[12:15], v[156:159], v[180:183], v[12:15]
	v_mfma_f32_16x16x32_bf16 v[12:15], v[160:163], v[184:187], v[12:15]
	v_mfma_f32_16x16x32_bf16 v[8:11], v[148:151], v[188:191], v[8:11]
	v_mfma_f32_16x16x32_bf16 v[8:11], v[152:155], v[192:195], v[8:11]
	v_mfma_f32_16x16x32_bf16 v[2:5], v[156:159], v[188:191], v[4:7]
	v_mfma_f32_16x16x32_bf16 v[2:5], v[160:163], v[192:195], v[2:5]
	s_barrier
	s_add_i32 s66, 0, 0x18000
	v_add_u32_e32 v0, s66, v228
	s_add_i32 s67, 0, 0x1c000
	ds_read_b128 v[132:135], v0
	ds_read_b128 v[136:139], v0 offset:1024
	ds_read_b128 v[140:143], v0 offset:2048
	ds_read_b128 v[144:147], v0 offset:3072
	v_add_u32_e32 v0, s67, v228
	ds_read_b128 v[148:151], v0
	ds_read_b128 v[152:155], v0 offset:1024
	ds_read_b128 v[156:159], v0 offset:2048
	ds_read_b128 v[160:163], v0 offset:3072
	s_mov_b32 m0, s46
	ds_read_b128 v[164:167], v230 offset:32768
	ds_read_b128 v[168:171], v230 offset:33792
	ds_read_b128 v[172:175], v230 offset:34816
	ds_read_b128 v[176:179], v230 offset:35840
	ds_read_b128 v[180:183], v230 offset:36864
	ds_read_b128 v[184:187], v230 offset:37888
	ds_read_b128 v[188:191], v230 offset:38912
	ds_read_b128 v[192:195], v230 offset:39936
	global_load_lds_dwordx4 v206, s[42:43]
	s_mov_b32 m0, s47
	s_nop 0
	global_load_lds_dwordx4 v202, s[42:43]
	s_add_u32 s42, s42, 0x80000
	s_addc_u32 s43, s43, 0
	s_mov_b32 m0, s48
	s_nop 0
	global_load_lds_dwordx4 v206, s[42:43]
	s_mov_b32 m0, s49
	s_nop 0
	global_load_lds_dwordx4 v202, s[42:43]
	s_waitcnt vmcnt(8)
	s_waitcnt lgkmcnt(0)
	s_barrier
	s_waitcnt lgkmcnt(0)
	v_mfma_f32_16x16x32_bf16 v[128:131], v[132:135], v[164:167], v[128:131]
	v_mfma_f32_16x16x32_bf16 v[128:131], v[136:139], v[168:171], v[128:131]
	v_mfma_f32_16x16x32_bf16 v[120:123], v[132:135], v[172:175], v[120:123]
	v_mfma_f32_16x16x32_bf16 v[120:123], v[136:139], v[176:179], v[120:123]
	v_mfma_f32_16x16x32_bf16 v[112:115], v[132:135], v[180:183], v[112:115]
	v_mfma_f32_16x16x32_bf16 v[112:115], v[136:139], v[184:187], v[112:115]
	v_mfma_f32_16x16x32_bf16 v[104:107], v[132:135], v[188:191], v[104:107]
	v_mfma_f32_16x16x32_bf16 v[104:107], v[136:139], v[192:195], v[104:107]
	v_mfma_f32_16x16x32_bf16 v[124:127], v[140:143], v[164:167], v[124:127]
	v_mfma_f32_16x16x32_bf16 v[124:127], v[144:147], v[168:171], v[124:127]
	v_mfma_f32_16x16x32_bf16 v[116:119], v[140:143], v[172:175], v[116:119]
	v_mfma_f32_16x16x32_bf16 v[116:119], v[144:147], v[176:179], v[116:119]
	v_mfma_f32_16x16x32_bf16 v[108:111], v[140:143], v[180:183], v[108:111]
	v_mfma_f32_16x16x32_bf16 v[108:111], v[144:147], v[184:187], v[108:111]
	v_mfma_f32_16x16x32_bf16 v[100:103], v[140:143], v[188:191], v[100:103]
	v_mfma_f32_16x16x32_bf16 v[100:103], v[144:147], v[192:195], v[100:103]
	v_mfma_f32_16x16x32_bf16 v[96:99], v[148:151], v[164:167], v[96:99]
	v_mfma_f32_16x16x32_bf16 v[96:99], v[152:155], v[168:171], v[96:99]
	v_mfma_f32_16x16x32_bf16 v[88:91], v[148:151], v[172:175], v[88:91]
	v_mfma_f32_16x16x32_bf16 v[88:91], v[152:155], v[176:179], v[88:91]
	v_mfma_f32_16x16x32_bf16 v[80:83], v[148:151], v[180:183], v[80:83]
	v_mfma_f32_16x16x32_bf16 v[80:83], v[152:155], v[184:187], v[80:83]
	v_mfma_f32_16x16x32_bf16 v[72:75], v[148:151], v[188:191], v[72:75]
	v_mfma_f32_16x16x32_bf16 v[72:75], v[152:155], v[192:195], v[72:75]
	v_mfma_f32_16x16x32_bf16 v[92:95], v[156:159], v[164:167], v[92:95]
	v_mfma_f32_16x16x32_bf16 v[92:95], v[160:163], v[168:171], v[92:95]
	v_mfma_f32_16x16x32_bf16 v[84:87], v[156:159], v[172:175], v[84:87]
	v_mfma_f32_16x16x32_bf16 v[84:87], v[160:163], v[176:179], v[84:87]
	v_mfma_f32_16x16x32_bf16 v[76:79], v[156:159], v[180:183], v[76:79]
	v_mfma_f32_16x16x32_bf16 v[76:79], v[160:163], v[184:187], v[76:79]
	v_mfma_f32_16x16x32_bf16 v[68:71], v[156:159], v[188:191], v[68:71]
	v_mfma_f32_16x16x32_bf16 v[68:71], v[160:163], v[192:195], v[68:71]
	s_barrier
	s_add_i32 s42, s66, s15
	s_add_u32 s98, s34, 0x80
	s_addc_u32 s99, s35, 0
	s_mov_b32 m0, s42
	ds_read_b128 v[164:167], v230 offset:49152
	ds_read_b128 v[168:171], v230 offset:50176
	ds_read_b128 v[172:175], v230 offset:51200
	ds_read_b128 v[176:179], v230 offset:52224
	ds_read_b128 v[180:183], v230 offset:53248
	ds_read_b128 v[184:187], v230 offset:54272
	ds_read_b128 v[188:191], v230 offset:55296
	ds_read_b128 v[192:195], v230 offset:56320
	global_load_lds_dwordx4 v204, s[98:99]
	s_add_i32 m0, s42, 0x2000
	s_add_u32 s34, s34, 0x80080
	s_addc_u32 s35, s35, 0
	s_add_i32 s42, s67, s15
	global_load_lds_dwordx4 v200, s[98:99]
	s_mov_b32 m0, s42
	s_nop 0
	global_load_lds_dwordx4 v204, s[34:35]
	s_add_i32 m0, s42, 0x2000
	s_nop 0
	global_load_lds_dwordx4 v200, s[34:35]
	s_waitcnt vmcnt(6)
	s_waitcnt lgkmcnt(0)
	s_barrier
	s_waitcnt lgkmcnt(0)
	v_mfma_f32_16x16x32_bf16 v[64:67], v[132:135], v[164:167], v[64:67]
	v_mfma_f32_16x16x32_bf16 v[64:67], v[136:139], v[168:171], v[64:67]
	v_mfma_f32_16x16x32_bf16 v[56:59], v[132:135], v[172:175], v[56:59]
	v_mfma_f32_16x16x32_bf16 v[56:59], v[136:139], v[176:179], v[56:59]
	v_mfma_f32_16x16x32_bf16 v[48:51], v[132:135], v[180:183], v[48:51]
	v_mfma_f32_16x16x32_bf16 v[48:51], v[136:139], v[184:187], v[48:51]
	v_mfma_f32_16x16x32_bf16 v[40:43], v[132:135], v[188:191], v[40:43]
	v_mfma_f32_16x16x32_bf16 v[40:43], v[136:139], v[192:195], v[40:43]
	v_mfma_f32_16x16x32_bf16 v[60:63], v[140:143], v[164:167], v[60:63]
	v_mfma_f32_16x16x32_bf16 v[60:63], v[144:147], v[168:171], v[60:63]
	v_mfma_f32_16x16x32_bf16 v[52:55], v[140:143], v[172:175], v[52:55]
	v_mfma_f32_16x16x32_bf16 v[52:55], v[144:147], v[176:179], v[52:55]
	v_mfma_f32_16x16x32_bf16 v[44:47], v[140:143], v[180:183], v[44:47]
	v_mfma_f32_16x16x32_bf16 v[44:47], v[144:147], v[184:187], v[44:47]
	v_mfma_f32_16x16x32_bf16 v[36:39], v[140:143], v[188:191], v[36:39]
	v_mfma_f32_16x16x32_bf16 v[36:39], v[144:147], v[192:195], v[36:39]
	v_mfma_f32_16x16x32_bf16 v[32:35], v[148:151], v[164:167], v[32:35]
	v_mfma_f32_16x16x32_bf16 v[32:35], v[152:155], v[168:171], v[32:35]
	v_mfma_f32_16x16x32_bf16 v[28:31], v[156:159], v[164:167], v[28:31]
	v_mfma_f32_16x16x32_bf16 v[28:31], v[160:163], v[168:171], v[28:31]
	v_mfma_f32_16x16x32_bf16 v[24:27], v[148:151], v[172:175], v[24:27]
	v_mfma_f32_16x16x32_bf16 v[24:27], v[152:155], v[176:179], v[24:27]
	v_mfma_f32_16x16x32_bf16 v[20:23], v[156:159], v[172:175], v[20:23]
	v_mfma_f32_16x16x32_bf16 v[20:23], v[160:163], v[176:179], v[20:23]
	v_mfma_f32_16x16x32_bf16 v[16:19], v[148:151], v[180:183], v[16:19]
	v_mfma_f32_16x16x32_bf16 v[16:19], v[152:155], v[184:187], v[16:19]
	v_mfma_f32_16x16x32_bf16 v[12:15], v[156:159], v[180:183], v[12:15]
	v_mfma_f32_16x16x32_bf16 v[12:15], v[160:163], v[184:187], v[12:15]
	v_mfma_f32_16x16x32_bf16 v[6:9], v[148:151], v[188:191], v[8:11]
	v_mfma_f32_16x16x32_bf16 v[8:11], v[152:155], v[192:195], v[6:9]
	v_mfma_f32_16x16x32_bf16 v[2:5], v[156:159], v[188:191], v[2:5]
	v_mfma_f32_16x16x32_bf16 v[4:7], v[160:163], v[192:195], v[2:5]
	s_barrier
	s_add_i32 s57, s57, 2
	s_add_u32 s30, s30, 0x100
	s_addc_u32 s31, s31, 0
	s_add_u32 s55, s55, 0x100
	s_addc_u32 s56, s56, 0
	s_cmp_gt_u32 s57, 29
	s_cbranch_scc0 .LBB0_577
	s_and_b64 vcc, exec, s[20:21]
	s_cbranch_vccz .LBB0_580
	s_barrier

.LBB0_587:
	s_mov_b32 s100, 0
	s_andn2_b64 vcc, exec, s[0:1]
	s_cbranch_vccnz .LBB0_568
	s_mov_b32 s100, 1
	s_branch .LBB0_568

.LBB0_769:
	v_readlane_b32 s34, v253, 46
	s_lshl_b32 s19, s19, 5
	v_readlane_b32 s35, v253, 47
	v_and_b32_e32 v9, 48, v8
	v_lshlrev_b32_e32 v18, 6, v8
	s_movk_i32 s21, 0x3c0
	v_lshlrev_b32_e32 v8, 2, v8
	s_and_b32 s49, s19, 0x60
	v_lshl_add_u64 v[10:11], s[34:35], 0, v[0:1]
	v_mov_b32_e32 v147, v1
	v_readlane_b32 s30, v253, 42
	s_lshl_b32 s48, s20, 6
	s_lshl_b32 s20, s20, 13
	v_and_or_b32 v9, v18, s21, v9
	v_and_b32_e32 v8, 32, v8
	s_lshl_b32 s19, s49, 7
	v_lshl_add_u64 v[12:13], s[34:35], 0, v[146:147]
	v_mov_b32_e32 v151, v1
	v_readlane_b32 s31, v253, 43
	v_bitop3_b32 v18, v9, s20, v8 bitop3:0xde
	v_bitop3_b32 v157, s19, v9, v8 bitop3:0xf6
	s_add_i32 m0, s14, 0x18000
	v_lshl_add_u64 v[8:9], v[10:11], 0, s[12:13]
	v_lshl_add_u64 v[14:15], s[30:31], 0, v[150:151]
	v_mov_b32_e32 v149, v1
	s_waitcnt vmcnt(2)
	s_barrier
	global_load_lds_dwordx4 v[8:9], off
	v_lshl_add_u64 v[8:9], v[12:13], 0, s[12:13]
	s_add_i32 m0, s14, 0x1a000
	s_add_i32 s50, s14, 0x8000
	v_lshl_add_u64 v[16:17], s[30:31], 0, v[148:149]
	global_load_lds_dwordx4 v[8:9], off
	v_lshl_add_u64 v[8:9], v[14:15], 0, s[12:13]
	s_mov_b32 m0, s50
	s_add_i32 s51, s14, 0xa000
	v_readlane_b32 s20, v253, 48
	global_load_lds_dwordx4 v[8:9], off
	v_lshl_add_u64 v[8:9], v[16:17], 0, s[12:13]
	s_mov_b32 m0, s51
	v_readlane_b32 s21, v253, 49
	global_load_lds_dwordx4 v[8:9], off
	s_add_i32 m0, s14, 0x1c000
	v_lshl_add_u64 v[8:9], s[20:21], 0, v[0:1]
	global_load_lds_dwordx4 v[8:9], off
	v_lshl_add_u64 v[8:9], s[20:21], 0, v[146:147]
	s_add_i32 m0, s14, 0x1e000
	s_cmpk_lt_u32 s18, 0x100
	global_load_lds_dwordx4 v[8:9], off
	v_lshlrev_b32_e32 v8, 15, v6
	v_and_b32_e32 v8, 0xffff0000, v8
	v_lshl_add_u32 v5, v5, 12, v8
	v_and_b32_e32 v6, 1, v6
	v_lshl_or_b32 v5, v6, 6, v5
	v_lshl_add_u32 v152, v7, 1, v5
	v_lshlrev_b32_e32 v5, 15, v2
	v_and_b32_e32 v5, 0xffff0000, v5
	s_waitcnt vmcnt(6)
	v_lshl_add_u32 v3, v3, 12, v5
	v_and_b32_e32 v2, 1, v2
	v_lshl_or_b32 v2, v2, 6, v3
	v_readlane_b32 s22, v253, 50
	s_cselect_b64 s[20:21], -1, 0
	v_mov_b32_e32 v153, v1
	v_lshl_add_u32 v154, v4, 1, v2
	v_mov_b32_e32 v155, v1
	s_mov_b32 s52, 0
	v_add_u32_e32 v161, 0, v18
	v_readlane_b32 s18, v253, 33
	s_mov_b32 s19, s22
	s_barrier
	v_readlane_b32 s23, v253, 51
	s_mov_b32 s100, 0
	s_branch .LBB0_772

.LBB0_778:
	s_ashr_i32 s25, s24, 31
	s_lshl_b64 s[26:27], s[24:25], 20
	v_readlane_b32 s23, v253, 40
	s_add_u32 s26, s23, s26
	v_readlane_b32 s23, v253, 41
	s_addc_u32 s27, s23, s27
	s_and_b64 s[28:29], s[40:41], exec
	s_cselect_b32 s25, s27, s31
	s_cselect_b32 s53, s26, s30
	s_ashr_i32 s23, s22, 31
	s_lshl_b64 s[28:29], s[22:23], 20
	v_readlane_b32 s23, v253, 34
	s_add_u32 s28, s23, s28
	v_readlane_b32 s23, v253, 35
	s_addc_u32 s29, s23, s29
	s_and_b64 s[42:43], s[40:41], exec
	s_cselect_b32 s23, s29, s35
	s_cselect_b32 s54, s28, s34
	s_add_u32 s30, s30, 0x80080
	s_addc_u32 s31, s31, 0
	s_add_u32 s55, s34, 0x100
	v_mov_b64_e32 v[2:3], 0
	v_mov_b64_e32 v[4:5], 0
	v_mov_b64_e32 v[6:7], 0
	v_mov_b64_e32 v[8:9], 0
	v_mov_b64_e32 v[10:11], 0
	v_mov_b64_e32 v[12:13], 0
	v_mov_b64_e32 v[14:15], 0
	v_mov_b64_e32 v[16:17], 0
	v_mov_b64_e32 v[18:19], 0
	v_mov_b64_e32 v[20:21], 0
	v_mov_b64_e32 v[22:23], 0
	v_mov_b64_e32 v[24:25], 0
	v_mov_b64_e32 v[26:27], 0
	v_mov_b64_e32 v[28:29], 0
	v_mov_b64_e32 v[30:31], 0
	v_mov_b64_e32 v[32:33], 0
	v_mov_b64_e32 v[34:35], 0
	v_mov_b64_e32 v[36:37], 0
	v_mov_b64_e32 v[38:39], 0
	v_mov_b64_e32 v[40:41], 0
	v_mov_b64_e32 v[42:43], 0
	v_mov_b64_e32 v[44:45], 0
	v_mov_b64_e32 v[46:47], 0
	v_mov_b64_e32 v[48:49], 0
	v_mov_b64_e32 v[50:51], 0
	v_mov_b64_e32 v[52:53], 0
	v_mov_b64_e32 v[54:55], 0
	v_mov_b64_e32 v[56:57], 0
	v_mov_b64_e32 v[58:59], 0
	v_mov_b64_e32 v[60:61], 0
	v_mov_b64_e32 v[62:63], 0
	v_mov_b64_e32 v[64:65], 0
	v_mov_b64_e32 v[66:67], 0
	v_mov_b64_e32 v[68:69], 0
	v_mov_b64_e32 v[70:71], 0
	v_mov_b64_e32 v[72:73], 0
	v_mov_b64_e32 v[74:75], 0
	v_mov_b64_e32 v[76:77], 0
	v_mov_b64_e32 v[78:79], 0
	v_mov_b64_e32 v[80:81], 0
	v_mov_b64_e32 v[82:83], 0
	v_mov_b64_e32 v[84:85], 0
	v_mov_b64_e32 v[86:87], 0
	v_mov_b64_e32 v[88:89], 0
	v_mov_b64_e32 v[98:99], 0
	v_mov_b64_e32 v[100:101], 0
	v_mov_b64_e32 v[102:103], 0
	v_mov_b64_e32 v[104:105], 0
	v_mov_b64_e32 v[110:111], 0
	v_mov_b64_e32 v[112:113], 0
	v_mov_b64_e32 v[118:119], 0
	v_mov_b64_e32 v[120:121], 0
	v_mov_b64_e32 v[122:123], 0
	v_mov_b64_e32 v[124:125], 0
	v_mov_b64_e32 v[126:127], 0
	v_mov_b64_e32 v[128:129], 0
	v_mov_b64_e32 v[130:131], 0
	v_mov_b64_e32 v[132:133], 0
	v_mov_b64_e32 v[134:135], 0
	v_mov_b64_e32 v[136:137], 0
	v_mov_b64_e32 v[138:139], 0
	v_mov_b64_e32 v[140:141], 0
	v_mov_b64_e32 v[142:143], 0
	v_mov_b64_e32 v[144:145], 0
	s_addc_u32 s56, s35, 0
	s_mov_b32 s57, -2
	s_cmp_eq_u32 s100, 1
	s_cbranch_scc0 .Lrb_skip_779
	s_barrier
.Lrb_skip_779:
.LBB0_779:
	s_add_u32 s98, s30, 0xfff80000
	s_addc_u32 s99, s31, -1
	s_add_u32 s34, s30, 0xfff80080
	s_addc_u32 s35, s31, -1
	s_add_i32 s66, 0, 0x10000
	s_cmp_eq_u32 s57, 28
	s_cselect_b32 s43, s25, s35
	s_cselect_b32 s42, s53, s34
	s_cselect_b32 s35, s23, s56
	s_cselect_b32 s34, s54, s55
	s_add_i32 s73, 0, 0x14000
	v_add_u32_e32 v114, s66, v157
	v_add_u32_e32 v156, s73, v157
	ds_read_b128 v[90:93], v114
	ds_read_b128 v[94:97], v114 offset:1024
	ds_read_b128 v[106:109], v114 offset:2048
	ds_read_b128 v[114:117], v114 offset:3072
	ds_read_b128 v[162:165], v156
	ds_read_b128 v[166:169], v156 offset:1024
	ds_read_b128 v[170:173], v156 offset:2048
	ds_read_b128 v[174:177], v156 offset:3072
	s_mov_b32 m0, s50
	ds_read_b128 v[178:181], v161
	ds_read_b128 v[182:185], v161 offset:1024
	ds_read_b128 v[186:189], v161 offset:2048
	ds_read_b128 v[190:193], v161 offset:3072
	ds_read_b128 v[200:203], v161 offset:4096
	ds_read_b128 v[204:207], v161 offset:5120
	ds_read_b128 v[208:211], v161 offset:6144
	ds_read_b128 v[212:215], v161 offset:7168
	global_load_lds_dwordx4 v150, s[98:99]
	s_mov_b32 m0, s51
	s_nop 0
	global_load_lds_dwordx4 v148, s[98:99]
	s_add_i32 m0, s14, 0xc000
	s_nop 0
	global_load_lds_dwordx4 v152, s[30:31]
	s_add_i32 m0, s14, 0xe000
	s_nop 0
	global_load_lds_dwordx4 v154, s[30:31]
	s_waitcnt vmcnt(8)
	s_waitcnt lgkmcnt(0)
	s_barrier
	s_waitcnt lgkmcnt(0)
	v_mfma_i32_16x16x64_i8 v[142:145], v[90:93], v[178:181], v[142:145]
	v_mfma_i32_16x16x64_i8 v[142:145], v[94:97], v[182:185], v[142:145]
	v_mfma_i32_16x16x64_i8 v[126:129], v[90:93], v[186:189], v[126:129]
	v_mfma_i32_16x16x64_i8 v[126:129], v[94:97], v[190:193], v[126:129]
	v_mfma_i32_16x16x64_i8 v[102:105], v[90:93], v[200:203], v[102:105]
	v_mfma_i32_16x16x64_i8 v[102:105], v[94:97], v[204:207], v[102:105]
	v_mfma_i32_16x16x64_i8 v[78:81], v[90:93], v[208:211], v[78:81]
	v_mfma_i32_16x16x64_i8 v[78:81], v[94:97], v[212:215], v[78:81]
	v_mfma_i32_16x16x64_i8 v[138:141], v[106:109], v[178:181], v[138:141]
	v_mfma_i32_16x16x64_i8 v[138:141], v[114:117], v[182:185], v[138:141]
	v_mfma_i32_16x16x64_i8 v[122:125], v[106:109], v[186:189], v[122:125]
	v_mfma_i32_16x16x64_i8 v[122:125], v[114:117], v[190:193], v[122:125]
	v_mfma_i32_16x16x64_i8 v[98:101], v[106:109], v[200:203], v[98:101]
	v_mfma_i32_16x16x64_i8 v[98:101], v[114:117], v[204:207], v[98:101]
	v_mfma_i32_16x16x64_i8 v[74:77], v[106:109], v[208:211], v[74:77]
	v_mfma_i32_16x16x64_i8 v[74:77], v[114:117], v[212:215], v[74:77]
	v_mfma_i32_16x16x64_i8 v[134:137], v[162:165], v[178:181], v[134:137]
	v_mfma_i32_16x16x64_i8 v[134:137], v[166:169], v[182:185], v[134:137]
	v_mfma_i32_16x16x64_i8 v[118:121], v[162:165], v[186:189], v[118:121]
	v_mfma_i32_16x16x64_i8 v[118:121], v[166:169], v[190:193], v[118:121]
	v_mfma_i32_16x16x64_i8 v[86:89], v[162:165], v[200:203], v[86:89]
	v_mfma_i32_16x16x64_i8 v[86:89], v[166:169], v[204:207], v[86:89]
	v_mfma_i32_16x16x64_i8 v[70:73], v[162:165], v[208:211], v[70:73]
	v_mfma_i32_16x16x64_i8 v[70:73], v[166:169], v[212:215], v[70:73]
	v_mfma_i32_16x16x64_i8 v[130:133], v[170:173], v[178:181], v[130:133]
	v_mfma_i32_16x16x64_i8 v[130:133], v[174:177], v[182:185], v[130:133]
	v_mfma_i32_16x16x64_i8 v[110:113], v[170:173], v[186:189], v[110:113]
	v_mfma_i32_16x16x64_i8 v[110:113], v[174:177], v[190:193], v[110:113]
	v_mfma_i32_16x16x64_i8 v[82:85], v[170:173], v[200:203], v[82:85]
	v_mfma_i32_16x16x64_i8 v[82:85], v[174:177], v[204:207], v[82:85]
	v_mfma_i32_16x16x64_i8 v[66:69], v[170:173], v[208:211], v[66:69]
	v_mfma_i32_16x16x64_i8 v[66:69], v[174:177], v[212:215], v[66:69]
	s_barrier
	s_add_i32 s66, s66, s9
	s_mov_b32 m0, s66
	ds_read_b128 v[178:181], v161 offset:16384
	ds_read_b128 v[182:185], v161 offset:17408
	ds_read_b128 v[186:189], v161 offset:18432
	ds_read_b128 v[190:193], v161 offset:19456
	ds_read_b128 v[200:203], v161 offset:20480
	ds_read_b128 v[204:207], v161 offset:21504
	ds_read_b128 v[208:211], v161 offset:22528
	ds_read_b128 v[212:215], v161 offset:23552
	global_load_lds_dwordx4 v0, s[34:35]
	s_add_i32 m0, s66, 0x2000
	s_add_u32 s66, s34, 0x80000
	s_addc_u32 s67, s35, 0
	s_add_i32 s73, s73, s9
	global_load_lds_dwordx4 v146, s[34:35]
	s_mov_b32 m0, s73
	s_nop 0
	global_load_lds_dwordx4 v0, s[66:67]
	s_add_i32 m0, s73, 0x2000
	s_nop 0
	global_load_lds_dwordx4 v146, s[66:67]
	s_waitcnt vmcnt(6)
	s_waitcnt lgkmcnt(0)
	s_barrier
	s_waitcnt lgkmcnt(0)
	v_mfma_i32_16x16x64_i8 v[62:65], v[90:93], v[178:181], v[62:65]
	v_mfma_i32_16x16x64_i8 v[62:65], v[94:97], v[182:185], v[62:65]
	v_mfma_i32_16x16x64_i8 v[46:49], v[90:93], v[186:189], v[46:49]
	v_mfma_i32_16x16x64_i8 v[46:49], v[94:97], v[190:193], v[46:49]
	v_mfma_i32_16x16x64_i8 v[30:33], v[90:93], v[200:203], v[30:33]
	v_mfma_i32_16x16x64_i8 v[30:33], v[94:97], v[204:207], v[30:33]
	v_mfma_i32_16x16x64_i8 v[14:17], v[90:93], v[208:211], v[14:17]
	v_mfma_i32_16x16x64_i8 v[14:17], v[94:97], v[212:215], v[14:17]
	v_mfma_i32_16x16x64_i8 v[58:61], v[106:109], v[178:181], v[58:61]
	v_mfma_i32_16x16x64_i8 v[58:61], v[114:117], v[182:185], v[58:61]
	v_mfma_i32_16x16x64_i8 v[42:45], v[106:109], v[186:189], v[42:45]
	v_mfma_i32_16x16x64_i8 v[42:45], v[114:117], v[190:193], v[42:45]
	v_mfma_i32_16x16x64_i8 v[26:29], v[106:109], v[200:203], v[26:29]
	v_mfma_i32_16x16x64_i8 v[26:29], v[114:117], v[204:207], v[26:29]
	v_mfma_i32_16x16x64_i8 v[10:13], v[106:109], v[208:211], v[10:13]
	v_mfma_i32_16x16x64_i8 v[10:13], v[114:117], v[212:215], v[10:13]
	v_mfma_i32_16x16x64_i8 v[54:57], v[162:165], v[178:181], v[54:57]
	v_mfma_i32_16x16x64_i8 v[54:57], v[166:169], v[182:185], v[54:57]
	v_mfma_i32_16x16x64_i8 v[38:41], v[162:165], v[186:189], v[38:41]
	v_mfma_i32_16x16x64_i8 v[38:41], v[166:169], v[190:193], v[38:41]
	v_mfma_i32_16x16x64_i8 v[22:25], v[162:165], v[200:203], v[22:25]
	v_mfma_i32_16x16x64_i8 v[22:25], v[166:169], v[204:207], v[22:25]
	v_mfma_i32_16x16x64_i8 v[6:9], v[162:165], v[208:211], v[6:9]
	v_mfma_i32_16x16x64_i8 v[6:9], v[166:169], v[212:215], v[6:9]
	v_mfma_i32_16x16x64_i8 v[50:53], v[170:173], v[178:181], v[50:53]
	v_mfma_i32_16x16x64_i8 v[50:53], v[174:177], v[182:185], v[50:53]
	v_mfma_i32_16x16x64_i8 v[34:37], v[170:173], v[186:189], v[34:37]
	v_mfma_i32_16x16x64_i8 v[34:37], v[174:177], v[190:193], v[34:37]
	v_mfma_i32_16x16x64_i8 v[18:21], v[170:173], v[200:203], v[18:21]
	v_mfma_i32_16x16x64_i8 v[18:21], v[174:177], v[204:207], v[18:21]
	v_mfma_i32_16x16x64_i8 v[2:5], v[170:173], v[208:211], v[2:5]
	v_mfma_i32_16x16x64_i8 v[2:5], v[174:177], v[212:215], v[2:5]
	s_barrier
	s_add_i32 s66, 0, 0x18000
	s_add_i32 s67, 0, 0x1c000
	v_add_u32_e32 v114, s66, v157
	v_add_u32_e32 v156, s67, v157
	ds_read_b128 v[90:93], v114
	ds_read_b128 v[94:97], v114 offset:1024
	ds_read_b128 v[106:109], v114 offset:2048
	ds_read_b128 v[114:117], v114 offset:3072
	ds_read_b128 v[162:165], v156
	ds_read_b128 v[166:169], v156 offset:1024
	ds_read_b128 v[170:173], v156 offset:2048
	ds_read_b128 v[174:177], v156 offset:3072
	s_mov_b32 m0, s14
	ds_read_b128 v[178:181], v161 offset:32768
	ds_read_b128 v[182:185], v161 offset:33792
	ds_read_b128 v[186:189], v161 offset:34816
	ds_read_b128 v[190:193], v161 offset:35840
	ds_read_b128 v[200:203], v161 offset:36864
	ds_read_b128 v[204:207], v161 offset:37888
	ds_read_b128 v[208:211], v161 offset:38912
	ds_read_b128 v[212:215], v161 offset:39936
	global_load_lds_dwordx4 v150, s[42:43]
	s_mov_b32 m0, s15
	s_nop 0
	global_load_lds_dwordx4 v148, s[42:43]
	s_add_u32 s42, s42, 0x80000
	s_addc_u32 s43, s43, 0
	s_mov_b32 m0, s46
	s_nop 0
	global_load_lds_dwordx4 v150, s[42:43]
	s_mov_b32 m0, s47
	s_nop 0
	global_load_lds_dwordx4 v148, s[42:43]
	s_waitcnt vmcnt(8)
	s_waitcnt lgkmcnt(0)
	s_barrier
	s_waitcnt lgkmcnt(0)
	v_mfma_i32_16x16x64_i8 v[142:145], v[90:93], v[178:181], v[142:145]
	v_mfma_i32_16x16x64_i8 v[142:145], v[94:97], v[182:185], v[142:145]
	v_mfma_i32_16x16x64_i8 v[126:129], v[90:93], v[186:189], v[126:129]
	v_mfma_i32_16x16x64_i8 v[126:129], v[94:97], v[190:193], v[126:129]
	v_mfma_i32_16x16x64_i8 v[102:105], v[90:93], v[200:203], v[102:105]
	v_mfma_i32_16x16x64_i8 v[102:105], v[94:97], v[204:207], v[102:105]
	v_mfma_i32_16x16x64_i8 v[78:81], v[90:93], v[208:211], v[78:81]
	v_mfma_i32_16x16x64_i8 v[78:81], v[94:97], v[212:215], v[78:81]
	v_mfma_i32_16x16x64_i8 v[138:141], v[106:109], v[178:181], v[138:141]
	v_mfma_i32_16x16x64_i8 v[138:141], v[114:117], v[182:185], v[138:141]
	v_mfma_i32_16x16x64_i8 v[122:125], v[106:109], v[186:189], v[122:125]
	v_mfma_i32_16x16x64_i8 v[122:125], v[114:117], v[190:193], v[122:125]
	v_mfma_i32_16x16x64_i8 v[98:101], v[106:109], v[200:203], v[98:101]
	v_mfma_i32_16x16x64_i8 v[98:101], v[114:117], v[204:207], v[98:101]
	v_mfma_i32_16x16x64_i8 v[74:77], v[106:109], v[208:211], v[74:77]
	v_mfma_i32_16x16x64_i8 v[74:77], v[114:117], v[212:215], v[74:77]
	v_mfma_i32_16x16x64_i8 v[134:137], v[162:165], v[178:181], v[134:137]
	v_mfma_i32_16x16x64_i8 v[134:137], v[166:169], v[182:185], v[134:137]
	v_mfma_i32_16x16x64_i8 v[118:121], v[162:165], v[186:189], v[118:121]
	v_mfma_i32_16x16x64_i8 v[118:121], v[166:169], v[190:193], v[118:121]
	v_mfma_i32_16x16x64_i8 v[86:89], v[162:165], v[200:203], v[86:89]
	v_mfma_i32_16x16x64_i8 v[86:89], v[166:169], v[204:207], v[86:89]
	v_mfma_i32_16x16x64_i8 v[70:73], v[162:165], v[208:211], v[70:73]
	v_mfma_i32_16x16x64_i8 v[70:73], v[166:169], v[212:215], v[70:73]
	v_mfma_i32_16x16x64_i8 v[130:133], v[170:173], v[178:181], v[130:133]
	v_mfma_i32_16x16x64_i8 v[130:133], v[174:177], v[182:185], v[130:133]
	v_mfma_i32_16x16x64_i8 v[110:113], v[170:173], v[186:189], v[110:113]
	v_mfma_i32_16x16x64_i8 v[110:113], v[174:177], v[190:193], v[110:113]
	v_mfma_i32_16x16x64_i8 v[82:85], v[170:173], v[200:203], v[82:85]
	v_mfma_i32_16x16x64_i8 v[82:85], v[174:177], v[204:207], v[82:85]
	v_mfma_i32_16x16x64_i8 v[66:69], v[170:173], v[208:211], v[66:69]
	v_mfma_i32_16x16x64_i8 v[66:69], v[174:177], v[212:215], v[66:69]
	s_barrier
	s_add_u32 s98, s34, 0x80
	s_addc_u32 s99, s35, 0
	s_add_i32 s42, s66, s9
	s_mov_b32 m0, s42
	ds_read_b128 v[178:181], v161 offset:49152
	ds_read_b128 v[182:185], v161 offset:50176
	ds_read_b128 v[186:189], v161 offset:51200
	ds_read_b128 v[190:193], v161 offset:52224
	ds_read_b128 v[200:203], v161 offset:53248
	ds_read_b128 v[204:207], v161 offset:54272
	ds_read_b128 v[208:211], v161 offset:55296
	ds_read_b128 v[212:215], v161 offset:56320
	global_load_lds_dwordx4 v0, s[98:99]
	s_add_i32 m0, s42, 0x2000
	s_add_u32 s34, s34, 0x80080
	s_addc_u32 s35, s35, 0
	s_add_i32 s42, s67, s9
	global_load_lds_dwordx4 v146, s[98:99]
	s_mov_b32 m0, s42
	s_nop 0
	global_load_lds_dwordx4 v0, s[34:35]
	s_add_i32 m0, s42, 0x2000
	s_nop 0
	global_load_lds_dwordx4 v146, s[34:35]
	s_waitcnt vmcnt(6)
	s_waitcnt lgkmcnt(0)
	s_barrier
	s_waitcnt lgkmcnt(0)
	v_mfma_i32_16x16x64_i8 v[62:65], v[90:93], v[178:181], v[62:65]
	v_mfma_i32_16x16x64_i8 v[62:65], v[94:97], v[182:185], v[62:65]
	v_mfma_i32_16x16x64_i8 v[46:49], v[90:93], v[186:189], v[46:49]
	v_mfma_i32_16x16x64_i8 v[46:49], v[94:97], v[190:193], v[46:49]
	v_mfma_i32_16x16x64_i8 v[30:33], v[90:93], v[200:203], v[30:33]
	v_mfma_i32_16x16x64_i8 v[30:33], v[94:97], v[204:207], v[30:33]
	v_mfma_i32_16x16x64_i8 v[14:17], v[90:93], v[208:211], v[14:17]
	v_mfma_i32_16x16x64_i8 v[14:17], v[94:97], v[212:215], v[14:17]
	v_mfma_i32_16x16x64_i8 v[58:61], v[106:109], v[178:181], v[58:61]
	v_mfma_i32_16x16x64_i8 v[58:61], v[114:117], v[182:185], v[58:61]
	v_mfma_i32_16x16x64_i8 v[42:45], v[106:109], v[186:189], v[42:45]
	v_mfma_i32_16x16x64_i8 v[42:45], v[114:117], v[190:193], v[42:45]
	v_mfma_i32_16x16x64_i8 v[26:29], v[106:109], v[200:203], v[26:29]
	v_mfma_i32_16x16x64_i8 v[26:29], v[114:117], v[204:207], v[26:29]
	v_mfma_i32_16x16x64_i8 v[10:13], v[106:109], v[208:211], v[10:13]
	v_mfma_i32_16x16x64_i8 v[10:13], v[114:117], v[212:215], v[10:13]
	v_mfma_i32_16x16x64_i8 v[54:57], v[162:165], v[178:181], v[54:57]
	v_mfma_i32_16x16x64_i8 v[54:57], v[166:169], v[182:185], v[54:57]
	v_mfma_i32_16x16x64_i8 v[38:41], v[162:165], v[186:189], v[38:41]
	v_mfma_i32_16x16x64_i8 v[38:41], v[166:169], v[190:193], v[38:41]
	v_mfma_i32_16x16x64_i8 v[22:25], v[162:165], v[200:203], v[22:25]
	v_mfma_i32_16x16x64_i8 v[22:25], v[166:169], v[204:207], v[22:25]
	v_mfma_i32_16x16x64_i8 v[6:9], v[162:165], v[208:211], v[6:9]
	v_mfma_i32_16x16x64_i8 v[6:9], v[166:169], v[212:215], v[6:9]
	v_mfma_i32_16x16x64_i8 v[50:53], v[170:173], v[178:181], v[50:53]
	v_mfma_i32_16x16x64_i8 v[50:53], v[174:177], v[182:185], v[50:53]
	v_mfma_i32_16x16x64_i8 v[34:37], v[170:173], v[186:189], v[34:37]
	v_mfma_i32_16x16x64_i8 v[34:37], v[174:177], v[190:193], v[34:37]
	v_mfma_i32_16x16x64_i8 v[18:21], v[170:173], v[200:203], v[18:21]
	v_mfma_i32_16x16x64_i8 v[18:21], v[174:177], v[204:207], v[18:21]
	v_mfma_i32_16x16x64_i8 v[2:5], v[170:173], v[208:211], v[2:5]
	v_mfma_i32_16x16x64_i8 v[2:5], v[174:177], v[212:215], v[2:5]
	s_barrier
	s_add_i32 s57, s57, 2
	s_add_u32 s30, s30, 0x100
	s_addc_u32 s31, s31, 0
	s_add_u32 s55, s55, 0x100
	s_addc_u32 s56, s56, 0
	s_cmp_gt_u32 s57, 29
	s_cbranch_scc0 .LBB0_779
	s_and_b64 vcc, exec, s[20:21]
	s_mov_b32 s54, 0x5c401000
	s_cbranch_vccz .LBB0_782
	s_barrier
.LBB0_782:
	v_mbcnt_lo_u32_b32 v156, -1, 0
	v_mbcnt_hi_u32_b32 v156, -1, v156
	s_lshl_b32 s19, s19, 8
	s_lshl_b32 s18, s18, 8
	v_ashrrev_i32_e32 v90, 1, v156
	s_add_i32 s19, s19, s48
	v_and_b32_e32 v90, -8, v90
	s_or_b32 s18, s18, s49
	v_add_u32_e32 v158, s18, v90
	v_and_or_b32 v172, v156, 15, s19
	v_readlane_b32 s18, v251, 37
	v_ashrrev_i32_e32 v159, 31, v158
	v_ashrrev_i32_e32 v173, 31, v172
	v_readlane_b32 s19, v251, 38
	v_lshl_add_u64 v[94:95], v[158:159], 2, s[44:45]
	global_load_dwordx4 v[106:109], v[94:95], off offset:16
	global_load_dwordx4 v[114:117], v[94:95], off
	global_load_dwordx4 v[90:93], v[94:95], off offset:528
	s_nop 0
	global_load_dwordx4 v[94:97], v[94:95], off offset:512
	v_lshl_add_u64 v[182:183], v[172:173], 2, s[18:19]
	global_load_dword v180, v[182:183], off
	v_or_b32_e32 v178, 16, v172
	v_ashrrev_i32_e32 v179, 31, v178
	v_lshl_add_u64 v[162:163], v[178:179], 2, s[18:19]
	global_load_dword v176, v[162:163], off
	v_or_b32_e32 v174, 32, v172
	v_ashrrev_i32_e32 v175, 31, v174
	v_lshl_add_u64 v[162:163], v[174:175], 2, s[18:19]
	global_load_dword v170, v[162:163], off
	v_or_b32_e32 v168, 48, v172
	v_ashrrev_i32_e32 v169, 31, v168
	v_lshl_add_u64 v[162:163], v[168:169], 2, s[18:19]
	global_load_dword v166, v[162:163], off
	global_load_dword v164, v[182:183], off offset:512
	s_nop 0
	global_load_dword v162, v[182:183], off offset:576
	global_load_dword v160, v[182:183], off offset:640
	global_load_dword v156, v[182:183], off offset:704
	v_readlane_b32 s18, v251, 35
	v_cvt_f32_i32_e32 v143, v143
	v_cvt_f32_i32_e32 v142, v142
	v_lshlrev_b64 v[172:173], 13, v[172:173]
	v_readlane_b32 s19, v251, 36
	v_cvt_f32_i32_e32 v145, v145
	v_cvt_f32_i32_e32 v144, v144
	v_lshl_add_u64 v[182:183], s[18:19], 0, v[172:173]
	v_lshlrev_b64 v[172:173], 1, v[158:159]
	v_cvt_f32_i32_e32 v139, v139
	v_cvt_f32_i32_e32 v138, v138
	s_waitcnt vmcnt(0)
	v_lshl_add_u64 v[158:159], v[182:183], 0, v[172:173]
	v_cvt_f32_i32_e32 v135, v135
	v_cvt_f32_i32_e32 v134, v134
	v_cvt_f32_i32_e32 v137, v137
	v_cvt_f32_i32_e32 v136, v136
	v_cvt_f32_i32_e32 v131, v131
	v_cvt_f32_i32_e32 v130, v130
	v_cvt_f32_i32_e32 v127, v127
	v_cvt_f32_i32_e32 v126, v126
	v_cvt_f32_i32_e32 v129, v129
	v_cvt_f32_i32_e32 v128, v128
	v_cvt_f32_i32_e32 v123, v123
	v_cvt_f32_i32_e32 v122, v122
	v_cvt_f32_i32_e32 v119, v119
	v_cvt_f32_i32_e32 v118, v118
	v_cvt_f32_i32_e32 v121, v121
	v_cvt_f32_i32_e32 v120, v120
	v_cvt_f32_i32_e32 v111, v111
	v_cvt_f32_i32_e32 v110, v110
	v_cvt_f32_i32_e32 v103, v103
	v_cvt_f32_i32_e32 v102, v102
	v_cvt_f32_i32_e32 v105, v105
	v_cvt_f32_i32_e32 v104, v104
	v_cvt_f32_i32_e32 v99, v99
	v_cvt_f32_i32_e32 v98, v98
	v_cvt_f32_i32_e32 v87, v87
	v_cvt_f32_i32_e32 v86, v86
	v_cvt_f32_i32_e32 v89, v89
	v_cvt_f32_i32_e32 v88, v88
	v_cvt_f32_i32_e32 v83, v83
	v_cvt_f32_i32_e32 v82, v82
	v_cvt_f32_i32_e32 v79, v79
	v_cvt_f32_i32_e32 v78, v78
	v_cvt_f32_i32_e32 v81, v81
	v_cvt_f32_i32_e32 v80, v80
	v_cvt_f32_i32_e32 v75, v75
	v_cvt_f32_i32_e32 v74, v74
	v_cvt_f32_i32_e32 v71, v71
	v_cvt_f32_i32_e32 v70, v70
	v_cvt_f32_i32_e32 v73, v73
	v_cvt_f32_i32_e32 v72, v72
	v_cvt_f32_i32_e32 v67, v67
	s_waitcnt vmcnt(0)
	s_nop 0
	v_pk_mul_f32 v[182:183], v[180:181], v[114:115] op_sel_hi:[0,1]
	v_pk_mul_f32 v[142:143], v[182:183], v[142:143]
	v_pk_mul_f32 v[182:183], v[180:181], v[116:117] op_sel_hi:[0,1]
	v_pk_mul_f32 v[144:145], v[182:183], v[144:145]
	v_pk_mul_f32 v[182:183], v[180:181], v[106:107] op_sel_hi:[0,1]
	v_pk_mul_f32 v[182:183], v[182:183], v[138:139]
	v_cvt_f32_i32_e32 v139, v141
	v_cvt_f32_i32_e32 v138, v140
	v_pk_mul_f32 v[140:141], v[180:181], v[108:109] op_sel_hi:[0,1]
	v_cvt_f32_i32_e32 v66, v66
	v_cvt_f32_i32_e32 v63, v63
	v_pk_mul_f32 v[184:185], v[140:141], v[138:139]
	v_cvt_pk_bf16_f32 v138, v142, v143
	v_cvt_pk_bf16_f32 v139, v144, v145
	v_cvt_pk_bf16_f32 v140, v182, v183
	v_cvt_pk_bf16_f32 v141, v184, v185
	global_store_dwordx4 v[158:159], v[138:141], off
	v_cvt_f32_i32_e32 v62, v62
	v_cvt_f32_i32_e32 v65, v65
	v_pk_mul_f32 v[138:139], v[180:181], v[94:95] op_sel_hi:[0,1]
	v_pk_mul_f32 v[134:135], v[138:139], v[134:135]
	v_pk_mul_f32 v[138:139], v[180:181], v[96:97] op_sel_hi:[0,1]
	v_pk_mul_f32 v[136:137], v[138:139], v[136:137]
	v_pk_mul_f32 v[138:139], v[180:181], v[90:91] op_sel_hi:[0,1]
	v_pk_mul_f32 v[138:139], v[138:139], v[130:131]
	v_cvt_f32_i32_e32 v131, v133
	v_cvt_f32_i32_e32 v130, v132
	v_pk_mul_f32 v[132:133], v[180:181], v[92:93] op_sel_hi:[0,1]
	v_cvt_f32_i32_e32 v64, v64
	v_cvt_f32_i32_e32 v59, v59
	v_pk_mul_f32 v[140:141], v[132:133], v[130:131]
	v_cvt_pk_bf16_f32 v130, v134, v135
	v_cvt_pk_bf16_f32 v131, v136, v137
	v_cvt_pk_bf16_f32 v132, v138, v139
	v_cvt_pk_bf16_f32 v133, v140, v141
	global_store_dwordx4 v[158:159], v[130:133], off offset:256
	v_cvt_f32_i32_e32 v58, v58
	v_cvt_f32_i32_e32 v55, v55
	v_pk_mul_f32 v[132:133], v[176:177], v[114:115] op_sel_hi:[0,1]
	v_pk_mul_f32 v[126:127], v[132:133], v[126:127]
	v_pk_mul_f32 v[132:133], v[176:177], v[116:117] op_sel_hi:[0,1]
	v_pk_mul_f32 v[128:129], v[132:133], v[128:129]
	v_pk_mul_f32 v[132:133], v[176:177], v[106:107] op_sel_hi:[0,1]
	v_pk_mul_f32 v[132:133], v[132:133], v[122:123]
	v_cvt_f32_i32_e32 v123, v125
	v_cvt_f32_i32_e32 v122, v124
	v_lshlrev_b64 v[130:131], 13, v[178:179]
	v_pk_mul_f32 v[124:125], v[176:177], v[108:109] op_sel_hi:[0,1]
	v_lshl_add_u64 v[130:131], s[18:19], 0, v[130:131]
	v_pk_mul_f32 v[134:135], v[124:125], v[122:123]
	v_lshl_add_u64 v[130:131], v[130:131], 0, v[172:173]
	v_cvt_pk_bf16_f32 v122, v126, v127
	v_cvt_pk_bf16_f32 v123, v128, v129
	v_cvt_pk_bf16_f32 v124, v132, v133
	v_cvt_pk_bf16_f32 v125, v134, v135
	global_store_dwordx4 v[130:131], v[122:125], off
	v_cvt_f32_i32_e32 v54, v54
	v_cvt_f32_i32_e32 v57, v57
	v_pk_mul_f32 v[122:123], v[176:177], v[94:95] op_sel_hi:[0,1]
	v_pk_mul_f32 v[118:119], v[122:123], v[118:119]
	v_pk_mul_f32 v[122:123], v[176:177], v[96:97] op_sel_hi:[0,1]
	v_pk_mul_f32 v[120:121], v[122:123], v[120:121]
	v_pk_mul_f32 v[122:123], v[176:177], v[90:91] op_sel_hi:[0,1]
	v_pk_mul_f32 v[122:123], v[122:123], v[110:111]
	v_cvt_f32_i32_e32 v111, v113
	v_cvt_f32_i32_e32 v110, v112
	v_pk_mul_f32 v[112:113], v[176:177], v[92:93] op_sel_hi:[0,1]
	v_cvt_f32_i32_e32 v56, v56
	v_cvt_f32_i32_e32 v51, v51
	v_pk_mul_f32 v[124:125], v[112:113], v[110:111]
	v_cvt_pk_bf16_f32 v110, v118, v119
	v_cvt_pk_bf16_f32 v111, v120, v121
	v_cvt_pk_bf16_f32 v112, v122, v123
	v_cvt_pk_bf16_f32 v113, v124, v125
	global_store_dwordx4 v[130:131], v[110:113], off offset:256
	v_cvt_f32_i32_e32 v50, v50
	v_cvt_f32_i32_e32 v47, v47
	v_pk_mul_f32 v[112:113], v[170:171], v[114:115] op_sel_hi:[0,1]
	v_pk_mul_f32 v[102:103], v[112:113], v[102:103]
	v_pk_mul_f32 v[112:113], v[170:171], v[116:117] op_sel_hi:[0,1]
	v_pk_mul_f32 v[104:105], v[112:113], v[104:105]
	v_pk_mul_f32 v[112:113], v[170:171], v[106:107] op_sel_hi:[0,1]
	v_pk_mul_f32 v[112:113], v[112:113], v[98:99]
	v_cvt_f32_i32_e32 v99, v101
	v_cvt_f32_i32_e32 v98, v100
	v_lshlrev_b64 v[110:111], 13, v[174:175]
	v_pk_mul_f32 v[100:101], v[170:171], v[108:109] op_sel_hi:[0,1]
	v_lshl_add_u64 v[110:111], s[18:19], 0, v[110:111]
	v_pk_mul_f32 v[118:119], v[100:101], v[98:99]
	v_lshl_add_u64 v[110:111], v[110:111], 0, v[172:173]
	v_cvt_pk_bf16_f32 v98, v102, v103
	v_cvt_pk_bf16_f32 v99, v104, v105
	v_cvt_pk_bf16_f32 v100, v112, v113
	v_cvt_pk_bf16_f32 v101, v118, v119
	global_store_dwordx4 v[110:111], v[98:101], off
	v_cvt_f32_i32_e32 v46, v46
	v_cvt_f32_i32_e32 v49, v49
	v_pk_mul_f32 v[98:99], v[170:171], v[94:95] op_sel_hi:[0,1]
	v_pk_mul_f32 v[86:87], v[98:99], v[86:87]
	v_pk_mul_f32 v[98:99], v[170:171], v[96:97] op_sel_hi:[0,1]
	v_pk_mul_f32 v[88:89], v[98:99], v[88:89]
	v_pk_mul_f32 v[98:99], v[170:171], v[90:91] op_sel_hi:[0,1]
	v_pk_mul_f32 v[98:99], v[98:99], v[82:83]
	v_cvt_f32_i32_e32 v83, v85
	v_cvt_f32_i32_e32 v82, v84
	v_pk_mul_f32 v[84:85], v[170:171], v[92:93] op_sel_hi:[0,1]
	v_cvt_f32_i32_e32 v48, v48
	v_cvt_f32_i32_e32 v43, v43
	v_pk_mul_f32 v[100:101], v[84:85], v[82:83]
	v_cvt_pk_bf16_f32 v82, v86, v87
	v_cvt_pk_bf16_f32 v83, v88, v89
	v_cvt_pk_bf16_f32 v84, v98, v99
	v_cvt_pk_bf16_f32 v85, v100, v101
	global_store_dwordx4 v[110:111], v[82:85], off offset:256
	v_cvt_f32_i32_e32 v42, v42
	v_cvt_f32_i32_e32 v39, v39
	v_pk_mul_f32 v[84:85], v[166:167], v[114:115] op_sel_hi:[0,1]
	v_pk_mul_f32 v[78:79], v[84:85], v[78:79]
	v_pk_mul_f32 v[84:85], v[166:167], v[116:117] op_sel_hi:[0,1]
	v_pk_mul_f32 v[80:81], v[84:85], v[80:81]
	v_pk_mul_f32 v[84:85], v[166:167], v[106:107] op_sel_hi:[0,1]
	v_pk_mul_f32 v[84:85], v[84:85], v[74:75]
	v_cvt_f32_i32_e32 v75, v77
	v_cvt_f32_i32_e32 v74, v76
	v_lshlrev_b64 v[82:83], 13, v[168:169]
	v_pk_mul_f32 v[76:77], v[166:167], v[108:109] op_sel_hi:[0,1]
	v_lshl_add_u64 v[82:83], s[18:19], 0, v[82:83]
	v_pk_mul_f32 v[86:87], v[76:77], v[74:75]
	v_lshl_add_u64 v[82:83], v[82:83], 0, v[172:173]
	v_cvt_pk_bf16_f32 v74, v78, v79
	v_cvt_pk_bf16_f32 v75, v80, v81
	v_cvt_pk_bf16_f32 v76, v84, v85
	v_cvt_pk_bf16_f32 v77, v86, v87
	global_store_dwordx4 v[82:83], v[74:77], off
	s_mov_b64 s[18:19], 0x100000
	v_cvt_f32_i32_e32 v38, v38
	v_pk_mul_f32 v[74:75], v[166:167], v[94:95] op_sel_hi:[0,1]
	v_pk_mul_f32 v[70:71], v[74:75], v[70:71]
	v_pk_mul_f32 v[74:75], v[166:167], v[96:97] op_sel_hi:[0,1]
	v_pk_mul_f32 v[72:73], v[74:75], v[72:73]
	v_pk_mul_f32 v[74:75], v[166:167], v[90:91] op_sel_hi:[0,1]
	v_pk_mul_f32 v[74:75], v[74:75], v[66:67]
	v_cvt_f32_i32_e32 v67, v69
	v_cvt_f32_i32_e32 v66, v68
	v_pk_mul_f32 v[68:69], v[166:167], v[92:93] op_sel_hi:[0,1]
	v_cvt_f32_i32_e32 v41, v41
	v_cvt_f32_i32_e32 v40, v40
	v_pk_mul_f32 v[76:77], v[68:69], v[66:67]
	v_cvt_pk_bf16_f32 v66, v70, v71
	v_cvt_pk_bf16_f32 v67, v72, v73
	v_cvt_pk_bf16_f32 v68, v74, v75
	v_cvt_pk_bf16_f32 v69, v76, v77
	global_store_dwordx4 v[82:83], v[66:69], off offset:256
	v_cvt_f32_i32_e32 v35, v35
	v_cvt_f32_i32_e32 v34, v34
	v_pk_mul_f32 v[68:69], v[164:165], v[114:115] op_sel_hi:[0,1]
	v_pk_mul_f32 v[62:63], v[68:69], v[62:63]
	v_pk_mul_f32 v[68:69], v[164:165], v[116:117] op_sel_hi:[0,1]
	v_pk_mul_f32 v[64:65], v[68:69], v[64:65]
	v_pk_mul_f32 v[68:69], v[164:165], v[106:107] op_sel_hi:[0,1]
	v_pk_mul_f32 v[68:69], v[68:69], v[58:59]
	v_cvt_f32_i32_e32 v59, v61
	v_cvt_f32_i32_e32 v58, v60
	v_lshl_add_u64 v[66:67], v[158:159], 0, s[18:19]
	v_pk_mul_f32 v[60:61], v[164:165], v[108:109] op_sel_hi:[0,1]
	s_mov_b32 s18, 0x100000
	v_pk_mul_f32 v[70:71], v[60:61], v[58:59]
	v_cvt_pk_bf16_f32 v58, v62, v63
	v_add_co_u32_e32 v62, vcc, s18, v158
	v_cvt_pk_bf16_f32 v59, v64, v65
	v_cvt_pk_bf16_f32 v60, v68, v69
	v_cvt_pk_bf16_f32 v61, v70, v71
	v_addc_co_u32_e32 v63, vcc, 0, v159, vcc
	global_store_dwordx4 v[62:63], v[58:61], off
	s_mov_b64 s[18:19], 0x120000
	v_cvt_f32_i32_e32 v31, v31
	v_pk_mul_f32 v[58:59], v[164:165], v[94:95] op_sel_hi:[0,1]
	v_pk_mul_f32 v[54:55], v[58:59], v[54:55]
	v_pk_mul_f32 v[58:59], v[164:165], v[96:97] op_sel_hi:[0,1]
	v_pk_mul_f32 v[56:57], v[58:59], v[56:57]
	v_pk_mul_f32 v[58:59], v[164:165], v[90:91] op_sel_hi:[0,1]
	v_pk_mul_f32 v[58:59], v[58:59], v[50:51]
	v_cvt_f32_i32_e32 v51, v53
	v_cvt_f32_i32_e32 v50, v52
	v_pk_mul_f32 v[52:53], v[164:165], v[92:93] op_sel_hi:[0,1]
	v_cvt_f32_i32_e32 v30, v30
	v_cvt_f32_i32_e32 v33, v33
	v_pk_mul_f32 v[60:61], v[52:53], v[50:51]
	v_cvt_pk_bf16_f32 v50, v54, v55
	v_cvt_pk_bf16_f32 v51, v56, v57
	v_cvt_pk_bf16_f32 v52, v58, v59
	v_cvt_pk_bf16_f32 v53, v60, v61
	global_store_dwordx4 v[66:67], v[50:53], off offset:256
	v_cvt_f32_i32_e32 v32, v32
	v_cvt_f32_i32_e32 v27, v27
	v_pk_mul_f32 v[52:53], v[162:163], v[114:115] op_sel_hi:[0,1]
	v_pk_mul_f32 v[46:47], v[52:53], v[46:47]
	v_pk_mul_f32 v[52:53], v[162:163], v[116:117] op_sel_hi:[0,1]
	v_pk_mul_f32 v[48:49], v[52:53], v[48:49]
	v_pk_mul_f32 v[52:53], v[162:163], v[106:107] op_sel_hi:[0,1]
	v_pk_mul_f32 v[52:53], v[52:53], v[42:43]
	v_cvt_f32_i32_e32 v43, v45
	v_cvt_f32_i32_e32 v42, v44
	v_lshl_add_u64 v[50:51], v[158:159], 0, s[18:19]
	v_pk_mul_f32 v[44:45], v[162:163], v[108:109] op_sel_hi:[0,1]
	s_mov_b32 s18, 0x120000
	v_pk_mul_f32 v[54:55], v[44:45], v[42:43]
	v_cvt_pk_bf16_f32 v42, v46, v47
	v_add_co_u32_e32 v46, vcc, s18, v158
	v_cvt_pk_bf16_f32 v43, v48, v49
	v_cvt_pk_bf16_f32 v44, v52, v53
	v_cvt_pk_bf16_f32 v45, v54, v55
	v_addc_co_u32_e32 v47, vcc, 0, v159, vcc
	global_store_dwordx4 v[46:47], v[42:45], off
	v_cvt_f32_i32_e32 v26, v26
	s_mov_b64 s[18:19], 0x140000
	v_pk_mul_f32 v[42:43], v[162:163], v[94:95] op_sel_hi:[0,1]
	v_pk_mul_f32 v[38:39], v[42:43], v[38:39]
	v_pk_mul_f32 v[42:43], v[162:163], v[96:97] op_sel_hi:[0,1]
	v_pk_mul_f32 v[40:41], v[42:43], v[40:41]
	v_pk_mul_f32 v[42:43], v[162:163], v[90:91] op_sel_hi:[0,1]
	v_pk_mul_f32 v[42:43], v[42:43], v[34:35]
	v_cvt_f32_i32_e32 v35, v37
	v_cvt_f32_i32_e32 v34, v36
	v_pk_mul_f32 v[36:37], v[162:163], v[92:93] op_sel_hi:[0,1]
	v_cvt_f32_i32_e32 v23, v23
	v_cvt_f32_i32_e32 v22, v22
	v_pk_mul_f32 v[44:45], v[36:37], v[34:35]
	v_cvt_pk_bf16_f32 v34, v38, v39
	v_cvt_pk_bf16_f32 v35, v40, v41
	v_cvt_pk_bf16_f32 v36, v42, v43
	v_cvt_pk_bf16_f32 v37, v44, v45
	global_store_dwordx4 v[50:51], v[34:37], off offset:256
	v_cvt_f32_i32_e32 v25, v25
	v_cvt_f32_i32_e32 v24, v24
	v_pk_mul_f32 v[36:37], v[160:161], v[114:115] op_sel_hi:[0,1]
	v_pk_mul_f32 v[30:31], v[36:37], v[30:31]
	v_pk_mul_f32 v[36:37], v[160:161], v[116:117] op_sel_hi:[0,1]
	v_pk_mul_f32 v[32:33], v[36:37], v[32:33]
	v_pk_mul_f32 v[36:37], v[160:161], v[106:107] op_sel_hi:[0,1]
	v_pk_mul_f32 v[36:37], v[36:37], v[26:27]
	v_cvt_f32_i32_e32 v27, v29
	v_cvt_f32_i32_e32 v26, v28
	v_lshl_add_u64 v[34:35], v[158:159], 0, s[18:19]
	v_pk_mul_f32 v[28:29], v[160:161], v[108:109] op_sel_hi:[0,1]
	s_mov_b32 s18, 0x140000
	v_pk_mul_f32 v[38:39], v[28:29], v[26:27]
	v_cvt_pk_bf16_f32 v26, v30, v31
	v_add_co_u32_e32 v30, vcc, s18, v158
	v_cvt_pk_bf16_f32 v27, v32, v33
	v_cvt_pk_bf16_f32 v28, v36, v37
	v_cvt_pk_bf16_f32 v29, v38, v39
	v_addc_co_u32_e32 v31, vcc, 0, v159, vcc
	v_cvt_f32_i32_e32 v19, v19
	v_cvt_f32_i32_e32 v18, v18
	global_store_dwordx4 v[30:31], v[26:29], off
	v_cvt_f32_i32_e32 v15, v15
	v_cvt_f32_i32_e32 v14, v14
	v_pk_mul_f32 v[26:27], v[160:161], v[94:95] op_sel_hi:[0,1]
	v_pk_mul_f32 v[22:23], v[26:27], v[22:23]
	v_pk_mul_f32 v[26:27], v[160:161], v[96:97] op_sel_hi:[0,1]
	v_pk_mul_f32 v[24:25], v[26:27], v[24:25]
	v_pk_mul_f32 v[26:27], v[160:161], v[90:91] op_sel_hi:[0,1]
	v_pk_mul_f32 v[26:27], v[26:27], v[18:19]
	v_cvt_f32_i32_e32 v19, v21
	v_cvt_f32_i32_e32 v18, v20
	v_pk_mul_f32 v[20:21], v[160:161], v[92:93] op_sel_hi:[0,1]
	v_cvt_f32_i32_e32 v17, v17
	v_cvt_f32_i32_e32 v16, v16
	v_pk_mul_f32 v[28:29], v[20:21], v[18:19]
	v_cvt_pk_bf16_f32 v18, v22, v23
	v_cvt_pk_bf16_f32 v19, v24, v25
	v_cvt_pk_bf16_f32 v20, v26, v27
	v_cvt_pk_bf16_f32 v21, v28, v29
	v_cvt_f32_i32_e32 v11, v11
	v_cvt_f32_i32_e32 v10, v10
	global_store_dwordx4 v[34:35], v[18:21], off offset:256
	s_mov_b64 s[18:19], 0x160000
	v_cvt_f32_i32_e32 v7, v7
	v_pk_mul_f32 v[20:21], v[156:157], v[114:115] op_sel_hi:[0,1]
	v_pk_mul_f32 v[14:15], v[20:21], v[14:15]
	v_pk_mul_f32 v[20:21], v[156:157], v[116:117] op_sel_hi:[0,1]
	v_pk_mul_f32 v[16:17], v[20:21], v[16:17]
	v_pk_mul_f32 v[20:21], v[156:157], v[106:107] op_sel_hi:[0,1]
	v_pk_mul_f32 v[20:21], v[20:21], v[10:11]
	v_cvt_f32_i32_e32 v11, v13
	v_cvt_f32_i32_e32 v10, v12
	v_lshl_add_u64 v[18:19], v[158:159], 0, s[18:19]
	v_pk_mul_f32 v[12:13], v[156:157], v[108:109] op_sel_hi:[0,1]
	s_mov_b32 s18, 0x160000
	v_cvt_f32_i32_e32 v6, v6
	v_pk_mul_f32 v[22:23], v[12:13], v[10:11]
	v_cvt_pk_bf16_f32 v10, v14, v15
	v_add_co_u32_e32 v14, vcc, s18, v158
	v_cvt_f32_i32_e32 v9, v9
	v_cvt_f32_i32_e32 v8, v8
	v_cvt_pk_bf16_f32 v11, v16, v17
	v_cvt_pk_bf16_f32 v12, v20, v21
	v_cvt_pk_bf16_f32 v13, v22, v23
	v_addc_co_u32_e32 v15, vcc, 0, v159, vcc
	v_cvt_f32_i32_e32 v3, v3
	v_cvt_f32_i32_e32 v2, v2
	global_store_dwordx4 v[14:15], v[10:13], off
	v_readlane_b32 s66, v255, 4
	s_mov_b64 s[30:31], -1
	v_pk_mul_f32 v[10:11], v[156:157], v[94:95] op_sel_hi:[0,1]
	v_pk_mul_f32 v[6:7], v[10:11], v[6:7]
	v_pk_mul_f32 v[10:11], v[156:157], v[96:97] op_sel_hi:[0,1]
	v_pk_mul_f32 v[8:9], v[10:11], v[8:9]
	v_pk_mul_f32 v[10:11], v[156:157], v[90:91] op_sel_hi:[0,1]
	v_pk_mul_f32 v[10:11], v[10:11], v[2:3]
	v_cvt_f32_i32_e32 v3, v5
	v_cvt_f32_i32_e32 v2, v4
	v_pk_mul_f32 v[4:5], v[156:157], v[92:93] op_sel_hi:[0,1]
	s_andn2_b64 vcc, exec, s[40:41]
	v_readlane_b32 s67, v255, 5
	v_pk_mul_f32 v[12:13], v[4:5], v[2:3]
	v_cvt_pk_bf16_f32 v2, v6, v7
	v_cvt_pk_bf16_f32 v3, v8, v9
	v_cvt_pk_bf16_f32 v4, v10, v11
	v_cvt_pk_bf16_f32 v5, v12, v13
	s_movk_i32 s57, 0x3000
	s_mov_b32 s73, 0xf800000
	global_store_dwordx4 v[18:19], v[2:5], off offset:256
	s_cbranch_vccnz .LBB0_771
	s_mov_b32 s100, 0
	s_andn2_b64 vcc, exec, s[0:1]
	s_cbranch_vccnz .LBB0_770
	s_mov_b32 s100, 1
	s_branch .LBB0_770

.LBB0_791:
	v_lshrrev_b32_e32 v18, 1, v8
	v_and_b32_e32 v18, 24, v18
	v_and_b32_e32 v9, 15, v8
	v_lshlrev_b32_e32 v19, 1, v18
	v_lshlrev_b32_e32 v8, 2, v8
	v_readlane_b32 s34, v253, 60
	v_lshl_or_b32 v140, s22, 6, v9
	v_lshl_or_b32 v9, v9, 6, v19
	s_lshl_b32 s22, s22, 13
	v_and_b32_e32 v8, 32, v8
	s_lshl_b32 s21, s21, 5
	v_readlane_b32 s35, v253, 61
	v_bitop3_b32 v19, v9, s22, v8 bitop3:0xde
	s_and_b32 s22, s21, 0x60
	v_lshl_add_u64 v[10:11], s[34:35], 0, v[0:1]
	v_mov_b32_e32 v131, v1
	v_readlane_b32 s30, v253, 56
	s_lshl_b32 s21, s22, 7
	v_lshl_add_u64 v[12:13], s[34:35], 0, v[130:131]
	v_mov_b32_e32 v135, v1
	v_readlane_b32 s31, v253, 57
	v_bitop3_b32 v141, v9, s21, v8 bitop3:0xde
	s_add_i32 m0, s14, 0x18000
	v_lshl_add_u64 v[8:9], v[10:11], 0, s[12:13]
	v_lshl_add_u64 v[14:15], s[30:31], 0, v[134:135]
	v_mov_b32_e32 v133, v1
	s_waitcnt vmcnt(2)
	s_barrier
	global_load_lds_dwordx4 v[8:9], off
	v_lshl_add_u64 v[8:9], v[12:13], 0, s[12:13]
	s_add_i32 m0, s14, 0x1a000
	s_add_i32 s42, s14, 0x8000
	v_lshl_add_u64 v[16:17], s[30:31], 0, v[132:133]
	global_load_lds_dwordx4 v[8:9], off
	v_lshl_add_u64 v[8:9], v[14:15], 0, s[12:13]
	s_mov_b32 m0, s42
	s_add_i32 s43, s14, 0xa000
	v_readlane_b32 s24, v253, 62
	global_load_lds_dwordx4 v[8:9], off
	v_lshl_add_u64 v[8:9], v[16:17], 0, s[12:13]
	s_mov_b32 m0, s43
	v_readlane_b32 s25, v253, 63
	global_load_lds_dwordx4 v[8:9], off
	s_add_i32 m0, s14, 0x1c000
	v_lshl_add_u64 v[8:9], s[24:25], 0, v[0:1]
	global_load_lds_dwordx4 v[8:9], off
	v_lshl_add_u64 v[8:9], s[24:25], 0, v[130:131]
	s_add_i32 m0, s14, 0x1e000
	s_cmpk_lt_u32 s20, 0x100
	global_load_lds_dwordx4 v[8:9], off
	v_lshlrev_b32_e32 v8, 16, v6
	v_and_b32_e32 v8, 0xfffe0000, v8
	v_lshl_add_u32 v5, v5, 13, v8
	v_and_b32_e32 v6, 1, v6
	v_lshl_or_b32 v5, v6, 6, v5
	v_lshl_add_u32 v136, v7, 1, v5
	v_lshlrev_b32_e32 v5, 16, v2
	v_and_b32_e32 v5, 0xfffe0000, v5
	s_waitcnt vmcnt(6)
	v_lshl_add_u32 v3, v3, 13, v5
	v_and_b32_e32 v2, 1, v2
	v_or_b32_e32 v142, s22, v18
	v_lshl_or_b32 v2, v2, 6, v3
	v_readlane_b32 s22, v253, 50
	s_cselect_b64 s[20:21], -1, 0
	v_mov_b32_e32 v137, v1
	v_lshl_add_u32 v138, v4, 1, v2
	v_mov_b32_e32 v139, v1
	s_mov_b32 s46, 0
	v_add_u32_e32 v143, 0, v19
	v_readlane_b32 s47, v253, 33
	s_mov_b32 s48, s22
	s_barrier
	v_readlane_b32 s23, v253, 51
	s_mov_b32 s100, 0
	s_branch .LBB0_794

.LBB0_800:
	s_ashr_i32 s25, s24, 31
	s_lshl_b64 s[26:27], s[24:25], 21
	s_add_u32 s26, s70, s26
	s_addc_u32 s27, s71, s27
	s_and_b64 s[28:29], s[38:39], exec
	s_cselect_b32 s25, s27, s31
	s_cselect_b32 s49, s26, s30
	s_ashr_i32 s23, s22, 31
	s_lshl_b64 s[28:29], s[22:23], 21
	v_readlane_b32 s23, v253, 52
	s_add_u32 s28, s23, s28
	v_readlane_b32 s23, v253, 53
	s_addc_u32 s29, s23, s29
	s_and_b64 s[40:41], s[38:39], exec
	s_cselect_b32 s23, s29, s35
	s_cselect_b32 s50, s28, s34
	s_add_u32 s30, s30, 0x100080
	s_addc_u32 s31, s31, 0
	s_add_u32 s51, s34, 0x100
	v_mov_b64_e32 v[2:3], 0
	v_mov_b64_e32 v[4:5], 0
	v_mov_b64_e32 v[6:7], 0
	v_mov_b64_e32 v[8:9], 0
	v_mov_b64_e32 v[10:11], 0
	v_mov_b64_e32 v[12:13], 0
	v_mov_b64_e32 v[14:15], 0
	v_mov_b64_e32 v[16:17], 0
	v_mov_b64_e32 v[18:19], 0
	v_mov_b64_e32 v[20:21], 0
	v_mov_b64_e32 v[22:23], 0
	v_mov_b64_e32 v[24:25], 0
	v_mov_b64_e32 v[26:27], 0
	v_mov_b64_e32 v[28:29], 0
	v_mov_b64_e32 v[30:31], 0
	v_mov_b64_e32 v[32:33], 0
	v_mov_b64_e32 v[34:35], 0
	v_mov_b64_e32 v[36:37], 0
	v_mov_b64_e32 v[38:39], 0
	v_mov_b64_e32 v[40:41], 0
	v_mov_b64_e32 v[42:43], 0
	v_mov_b64_e32 v[44:45], 0
	v_mov_b64_e32 v[46:47], 0
	v_mov_b64_e32 v[48:49], 0
	v_mov_b64_e32 v[50:51], 0
	v_mov_b64_e32 v[52:53], 0
	v_mov_b64_e32 v[54:55], 0
	v_mov_b64_e32 v[56:57], 0
	v_mov_b64_e32 v[58:59], 0
	v_mov_b64_e32 v[60:61], 0
	v_mov_b64_e32 v[62:63], 0
	v_mov_b64_e32 v[64:65], 0
	v_mov_b64_e32 v[66:67], 0
	v_mov_b64_e32 v[68:69], 0
	v_mov_b64_e32 v[70:71], 0
	v_mov_b64_e32 v[72:73], 0
	v_mov_b64_e32 v[74:75], 0
	v_mov_b64_e32 v[76:77], 0
	v_mov_b64_e32 v[78:79], 0
	v_mov_b64_e32 v[80:81], 0
	v_mov_b64_e32 v[82:83], 0
	v_mov_b64_e32 v[84:85], 0
	v_mov_b64_e32 v[86:87], 0
	v_mov_b64_e32 v[88:89], 0
	v_mov_b64_e32 v[90:91], 0
	v_mov_b64_e32 v[92:93], 0
	v_mov_b64_e32 v[94:95], 0
	v_mov_b64_e32 v[96:97], 0
	v_mov_b64_e32 v[98:99], 0
	v_mov_b64_e32 v[100:101], 0
	v_mov_b64_e32 v[102:103], 0
	v_mov_b64_e32 v[104:105], 0
	v_mov_b64_e32 v[106:107], 0
	v_mov_b64_e32 v[108:109], 0
	v_mov_b64_e32 v[110:111], 0
	v_mov_b64_e32 v[112:113], 0
	v_mov_b64_e32 v[114:115], 0
	v_mov_b64_e32 v[116:117], 0
	v_mov_b64_e32 v[118:119], 0
	v_mov_b64_e32 v[120:121], 0
	v_mov_b64_e32 v[122:123], 0
	v_mov_b64_e32 v[124:125], 0
	v_mov_b64_e32 v[126:127], 0
	v_mov_b64_e32 v[128:129], 0
	s_addc_u32 s52, s35, 0
	s_mov_b32 s53, -2
	s_cmp_eq_u32 s100, 1
	s_cbranch_scc0 .Lrb_skip_801
	s_barrier
.Lrb_skip_801:
.LBB0_801:
	s_add_u32 s98, s30, 0xfff00000
	s_addc_u32 s99, s31, -1
	s_add_u32 s34, s30, 0xfff00080
	s_addc_u32 s35, s31, -1
	s_add_i32 s54, 0, 0x10000
	s_cmp_eq_u32 s53, 60
	s_cselect_b32 s41, s25, s35
	s_cselect_b32 s40, s49, s34
	s_cselect_b32 s35, s23, s52
	s_cselect_b32 s34, s50, s51
	s_add_i32 s56, 0, 0x14000
	v_add_u32_e32 v156, s54, v141
	v_add_u32_e32 v172, s56, v141
	ds_read_b128 v[144:147], v156
	ds_read_b128 v[148:151], v156 offset:1024
	ds_read_b128 v[152:155], v156 offset:2048
	ds_read_b128 v[156:159], v156 offset:3072
	ds_read_b128 v[160:163], v172
	ds_read_b128 v[164:167], v172 offset:1024
	ds_read_b128 v[168:171], v172 offset:2048
	ds_read_b128 v[172:175], v172 offset:3072
	s_mov_b32 m0, s42
	ds_read_b128 v[176:179], v143
	ds_read_b128 v[180:183], v143 offset:1024
	ds_read_b128 v[184:187], v143 offset:2048
	ds_read_b128 v[188:191], v143 offset:3072
	ds_read_b128 v[192:195], v143 offset:4096
	ds_read_b128 v[200:203], v143 offset:5120
	ds_read_b128 v[204:207], v143 offset:6144
	ds_read_b128 v[208:211], v143 offset:7168
	global_load_lds_dwordx4 v134, s[98:99]
	s_mov_b32 m0, s43
	s_nop 0
	global_load_lds_dwordx4 v132, s[98:99]
	s_add_i32 m0, s14, 0xc000
	s_nop 0
	global_load_lds_dwordx4 v136, s[30:31]
	s_add_i32 m0, s14, 0xe000
	s_nop 0
	global_load_lds_dwordx4 v138, s[30:31]
	s_waitcnt vmcnt(8)
	s_waitcnt lgkmcnt(0)
	s_barrier
	s_waitcnt lgkmcnt(0)
	v_mfma_f32_16x16x32_bf16 v[126:129], v[144:147], v[176:179], v[126:129]
	v_mfma_f32_16x16x32_bf16 v[126:129], v[148:151], v[180:183], v[126:129]
	v_mfma_f32_16x16x32_bf16 v[118:121], v[144:147], v[184:187], v[118:121]
	v_mfma_f32_16x16x32_bf16 v[118:121], v[148:151], v[188:191], v[118:121]
	v_mfma_f32_16x16x32_bf16 v[102:105], v[144:147], v[192:195], v[102:105]
	v_mfma_f32_16x16x32_bf16 v[102:105], v[148:151], v[200:203], v[102:105]
	v_mfma_f32_16x16x32_bf16 v[86:89], v[144:147], v[204:207], v[86:89]
	v_mfma_f32_16x16x32_bf16 v[86:89], v[148:151], v[208:211], v[86:89]
	v_mfma_f32_16x16x32_bf16 v[122:125], v[152:155], v[176:179], v[122:125]
	v_mfma_f32_16x16x32_bf16 v[122:125], v[156:159], v[180:183], v[122:125]
	v_mfma_f32_16x16x32_bf16 v[114:117], v[152:155], v[184:187], v[114:117]
	v_mfma_f32_16x16x32_bf16 v[114:117], v[156:159], v[188:191], v[114:117]
	v_mfma_f32_16x16x32_bf16 v[98:101], v[152:155], v[192:195], v[98:101]
	v_mfma_f32_16x16x32_bf16 v[98:101], v[156:159], v[200:203], v[98:101]
	v_mfma_f32_16x16x32_bf16 v[82:85], v[152:155], v[204:207], v[82:85]
	v_mfma_f32_16x16x32_bf16 v[82:85], v[156:159], v[208:211], v[82:85]
	v_mfma_f32_16x16x32_bf16 v[110:113], v[160:163], v[176:179], v[110:113]
	v_mfma_f32_16x16x32_bf16 v[110:113], v[164:167], v[180:183], v[110:113]
	v_mfma_f32_16x16x32_bf16 v[94:97], v[160:163], v[184:187], v[94:97]
	v_mfma_f32_16x16x32_bf16 v[94:97], v[164:167], v[188:191], v[94:97]
	v_mfma_f32_16x16x32_bf16 v[78:81], v[160:163], v[192:195], v[78:81]
	v_mfma_f32_16x16x32_bf16 v[78:81], v[164:167], v[200:203], v[78:81]
	v_mfma_f32_16x16x32_bf16 v[70:73], v[160:163], v[204:207], v[70:73]
	v_mfma_f32_16x16x32_bf16 v[70:73], v[164:167], v[208:211], v[70:73]
	v_mfma_f32_16x16x32_bf16 v[106:109], v[168:171], v[176:179], v[106:109]
	v_mfma_f32_16x16x32_bf16 v[106:109], v[172:175], v[180:183], v[106:109]
	v_mfma_f32_16x16x32_bf16 v[90:93], v[168:171], v[184:187], v[90:93]
	v_mfma_f32_16x16x32_bf16 v[90:93], v[172:175], v[188:191], v[90:93]
	v_mfma_f32_16x16x32_bf16 v[74:77], v[168:171], v[192:195], v[74:77]
	v_mfma_f32_16x16x32_bf16 v[74:77], v[172:175], v[200:203], v[74:77]
	v_mfma_f32_16x16x32_bf16 v[66:69], v[168:171], v[204:207], v[66:69]
	v_mfma_f32_16x16x32_bf16 v[66:69], v[172:175], v[208:211], v[66:69]
	s_barrier
	s_add_i32 s54, s54, s9
	s_mov_b32 m0, s54
	ds_read_b128 v[176:179], v143 offset:16384
	ds_read_b128 v[180:183], v143 offset:17408
	ds_read_b128 v[184:187], v143 offset:18432
	ds_read_b128 v[188:191], v143 offset:19456
	ds_read_b128 v[192:195], v143 offset:20480
	ds_read_b128 v[200:203], v143 offset:21504
	ds_read_b128 v[204:207], v143 offset:22528
	ds_read_b128 v[208:211], v143 offset:23552
	global_load_lds_dwordx4 v0, s[34:35]
	s_add_i32 m0, s54, 0x2000
	s_add_u32 s54, s34, 0x100000
	s_addc_u32 s55, s35, 0
	s_add_i32 s56, s56, s9
	global_load_lds_dwordx4 v130, s[34:35]
	s_mov_b32 m0, s56
	s_nop 0
	global_load_lds_dwordx4 v0, s[54:55]
	s_add_i32 m0, s56, 0x2000
	s_nop 0
	global_load_lds_dwordx4 v130, s[54:55]
	s_waitcnt vmcnt(6)
	s_waitcnt lgkmcnt(0)
	s_barrier
	s_waitcnt lgkmcnt(0)
	v_mfma_f32_16x16x32_bf16 v[62:65], v[144:147], v[176:179], v[62:65]
	v_mfma_f32_16x16x32_bf16 v[62:65], v[148:151], v[180:183], v[62:65]
	v_mfma_f32_16x16x32_bf16 v[54:57], v[144:147], v[184:187], v[54:57]
	v_mfma_f32_16x16x32_bf16 v[54:57], v[148:151], v[188:191], v[54:57]
	v_mfma_f32_16x16x32_bf16 v[38:41], v[144:147], v[192:195], v[38:41]
	v_mfma_f32_16x16x32_bf16 v[38:41], v[148:151], v[200:203], v[38:41]
	v_mfma_f32_16x16x32_bf16 v[22:25], v[144:147], v[204:207], v[22:25]
	v_mfma_f32_16x16x32_bf16 v[22:25], v[148:151], v[208:211], v[22:25]
	v_mfma_f32_16x16x32_bf16 v[58:61], v[152:155], v[176:179], v[58:61]
	v_mfma_f32_16x16x32_bf16 v[58:61], v[156:159], v[180:183], v[58:61]
	v_mfma_f32_16x16x32_bf16 v[50:53], v[152:155], v[184:187], v[50:53]
	v_mfma_f32_16x16x32_bf16 v[50:53], v[156:159], v[188:191], v[50:53]
	v_mfma_f32_16x16x32_bf16 v[34:37], v[152:155], v[192:195], v[34:37]
	v_mfma_f32_16x16x32_bf16 v[34:37], v[156:159], v[200:203], v[34:37]
	v_mfma_f32_16x16x32_bf16 v[18:21], v[152:155], v[204:207], v[18:21]
	v_mfma_f32_16x16x32_bf16 v[18:21], v[156:159], v[208:211], v[18:21]
	v_mfma_f32_16x16x32_bf16 v[46:49], v[160:163], v[176:179], v[46:49]
	v_mfma_f32_16x16x32_bf16 v[46:49], v[164:167], v[180:183], v[46:49]
	v_mfma_f32_16x16x32_bf16 v[30:33], v[160:163], v[184:187], v[30:33]
	v_mfma_f32_16x16x32_bf16 v[30:33], v[164:167], v[188:191], v[30:33]
	v_mfma_f32_16x16x32_bf16 v[14:17], v[160:163], v[192:195], v[14:17]
	v_mfma_f32_16x16x32_bf16 v[14:17], v[164:167], v[200:203], v[14:17]
	v_mfma_f32_16x16x32_bf16 v[6:9], v[160:163], v[204:207], v[6:9]
	v_mfma_f32_16x16x32_bf16 v[6:9], v[164:167], v[208:211], v[6:9]
	v_mfma_f32_16x16x32_bf16 v[42:45], v[168:171], v[176:179], v[42:45]
	v_mfma_f32_16x16x32_bf16 v[42:45], v[172:175], v[180:183], v[42:45]
	v_mfma_f32_16x16x32_bf16 v[26:29], v[168:171], v[184:187], v[26:29]
	v_mfma_f32_16x16x32_bf16 v[26:29], v[172:175], v[188:191], v[26:29]
	v_mfma_f32_16x16x32_bf16 v[10:13], v[168:171], v[192:195], v[10:13]
	v_mfma_f32_16x16x32_bf16 v[10:13], v[172:175], v[200:203], v[10:13]
	v_mfma_f32_16x16x32_bf16 v[2:5], v[168:171], v[204:207], v[2:5]
	v_mfma_f32_16x16x32_bf16 v[2:5], v[172:175], v[208:211], v[2:5]
	s_barrier
	s_add_i32 s54, 0, 0x18000
	s_add_i32 s55, 0, 0x1c000
	v_add_u32_e32 v156, s54, v141
	v_add_u32_e32 v172, s55, v141
	ds_read_b128 v[144:147], v156
	ds_read_b128 v[148:151], v156 offset:1024
	ds_read_b128 v[152:155], v156 offset:2048
	ds_read_b128 v[156:159], v156 offset:3072
	ds_read_b128 v[160:163], v172
	ds_read_b128 v[164:167], v172 offset:1024
	ds_read_b128 v[168:171], v172 offset:2048
	ds_read_b128 v[172:175], v172 offset:3072
	s_mov_b32 m0, s14
	ds_read_b128 v[176:179], v143 offset:32768
	ds_read_b128 v[180:183], v143 offset:33792
	ds_read_b128 v[184:187], v143 offset:34816
	ds_read_b128 v[188:191], v143 offset:35840
	ds_read_b128 v[192:195], v143 offset:36864
	ds_read_b128 v[200:203], v143 offset:37888
	ds_read_b128 v[204:207], v143 offset:38912
	ds_read_b128 v[208:211], v143 offset:39936
	global_load_lds_dwordx4 v134, s[40:41]
	s_mov_b32 m0, s15
	s_nop 0
	global_load_lds_dwordx4 v132, s[40:41]
	s_add_u32 s40, s40, 0x100000
	s_addc_u32 s41, s41, 0
	s_mov_b32 m0, s18
	s_nop 0
	global_load_lds_dwordx4 v134, s[40:41]
	s_mov_b32 m0, s19
	s_nop 0
	global_load_lds_dwordx4 v132, s[40:41]
	s_waitcnt vmcnt(8)
	s_waitcnt lgkmcnt(0)
	s_barrier
	s_waitcnt lgkmcnt(0)
	v_mfma_f32_16x16x32_bf16 v[126:129], v[144:147], v[176:179], v[126:129]
	v_mfma_f32_16x16x32_bf16 v[126:129], v[148:151], v[180:183], v[126:129]
	v_mfma_f32_16x16x32_bf16 v[118:121], v[144:147], v[184:187], v[118:121]
	v_mfma_f32_16x16x32_bf16 v[118:121], v[148:151], v[188:191], v[118:121]
	v_mfma_f32_16x16x32_bf16 v[102:105], v[144:147], v[192:195], v[102:105]
	v_mfma_f32_16x16x32_bf16 v[102:105], v[148:151], v[200:203], v[102:105]
	v_mfma_f32_16x16x32_bf16 v[86:89], v[144:147], v[204:207], v[86:89]
	v_mfma_f32_16x16x32_bf16 v[86:89], v[148:151], v[208:211], v[86:89]
	v_mfma_f32_16x16x32_bf16 v[122:125], v[152:155], v[176:179], v[122:125]
	v_mfma_f32_16x16x32_bf16 v[122:125], v[156:159], v[180:183], v[122:125]
	v_mfma_f32_16x16x32_bf16 v[114:117], v[152:155], v[184:187], v[114:117]
	v_mfma_f32_16x16x32_bf16 v[114:117], v[156:159], v[188:191], v[114:117]
	v_mfma_f32_16x16x32_bf16 v[98:101], v[152:155], v[192:195], v[98:101]
	v_mfma_f32_16x16x32_bf16 v[98:101], v[156:159], v[200:203], v[98:101]
	v_mfma_f32_16x16x32_bf16 v[82:85], v[152:155], v[204:207], v[82:85]
	v_mfma_f32_16x16x32_bf16 v[82:85], v[156:159], v[208:211], v[82:85]
	v_mfma_f32_16x16x32_bf16 v[110:113], v[160:163], v[176:179], v[110:113]
	v_mfma_f32_16x16x32_bf16 v[110:113], v[164:167], v[180:183], v[110:113]
	v_mfma_f32_16x16x32_bf16 v[94:97], v[160:163], v[184:187], v[94:97]
	v_mfma_f32_16x16x32_bf16 v[94:97], v[164:167], v[188:191], v[94:97]
	v_mfma_f32_16x16x32_bf16 v[78:81], v[160:163], v[192:195], v[78:81]
	v_mfma_f32_16x16x32_bf16 v[78:81], v[164:167], v[200:203], v[78:81]
	v_mfma_f32_16x16x32_bf16 v[70:73], v[160:163], v[204:207], v[70:73]
	v_mfma_f32_16x16x32_bf16 v[70:73], v[164:167], v[208:211], v[70:73]
	v_mfma_f32_16x16x32_bf16 v[106:109], v[168:171], v[176:179], v[106:109]
	v_mfma_f32_16x16x32_bf16 v[106:109], v[172:175], v[180:183], v[106:109]
	v_mfma_f32_16x16x32_bf16 v[90:93], v[168:171], v[184:187], v[90:93]
	v_mfma_f32_16x16x32_bf16 v[90:93], v[172:175], v[188:191], v[90:93]
	v_mfma_f32_16x16x32_bf16 v[74:77], v[168:171], v[192:195], v[74:77]
	v_mfma_f32_16x16x32_bf16 v[74:77], v[172:175], v[200:203], v[74:77]
	v_mfma_f32_16x16x32_bf16 v[66:69], v[168:171], v[204:207], v[66:69]
	v_mfma_f32_16x16x32_bf16 v[66:69], v[172:175], v[208:211], v[66:69]
	s_barrier
	s_add_u32 s98, s34, 0x80
	s_addc_u32 s99, s35, 0
	s_add_i32 s40, s54, s9
	s_mov_b32 m0, s40
	ds_read_b128 v[176:179], v143 offset:49152
	ds_read_b128 v[180:183], v143 offset:50176
	ds_read_b128 v[184:187], v143 offset:51200
	ds_read_b128 v[188:191], v143 offset:52224
	ds_read_b128 v[192:195], v143 offset:53248
	ds_read_b128 v[200:203], v143 offset:54272
	ds_read_b128 v[204:207], v143 offset:55296
	ds_read_b128 v[208:211], v143 offset:56320
	global_load_lds_dwordx4 v0, s[98:99]
	s_add_i32 m0, s40, 0x2000
	s_add_u32 s34, s34, 0x100080
	s_addc_u32 s35, s35, 0
	s_add_i32 s40, s55, s9
	global_load_lds_dwordx4 v130, s[98:99]
	s_mov_b32 m0, s40
	s_nop 0
	global_load_lds_dwordx4 v0, s[34:35]
	s_add_i32 m0, s40, 0x2000
	s_nop 0
	global_load_lds_dwordx4 v130, s[34:35]
	s_waitcnt vmcnt(6)
	s_waitcnt lgkmcnt(0)
	s_barrier
	s_waitcnt lgkmcnt(0)
	v_mfma_f32_16x16x32_bf16 v[62:65], v[144:147], v[176:179], v[62:65]
	v_mfma_f32_16x16x32_bf16 v[62:65], v[148:151], v[180:183], v[62:65]
	v_mfma_f32_16x16x32_bf16 v[54:57], v[144:147], v[184:187], v[54:57]
	v_mfma_f32_16x16x32_bf16 v[54:57], v[148:151], v[188:191], v[54:57]
	v_mfma_f32_16x16x32_bf16 v[38:41], v[144:147], v[192:195], v[38:41]
	v_mfma_f32_16x16x32_bf16 v[38:41], v[148:151], v[200:203], v[38:41]
	v_mfma_f32_16x16x32_bf16 v[22:25], v[144:147], v[204:207], v[22:25]
	v_mfma_f32_16x16x32_bf16 v[22:25], v[148:151], v[208:211], v[22:25]
	v_mfma_f32_16x16x32_bf16 v[58:61], v[152:155], v[176:179], v[58:61]
	v_mfma_f32_16x16x32_bf16 v[58:61], v[156:159], v[180:183], v[58:61]
	v_mfma_f32_16x16x32_bf16 v[50:53], v[152:155], v[184:187], v[50:53]
	v_mfma_f32_16x16x32_bf16 v[50:53], v[156:159], v[188:191], v[50:53]
	v_mfma_f32_16x16x32_bf16 v[34:37], v[152:155], v[192:195], v[34:37]
	v_mfma_f32_16x16x32_bf16 v[34:37], v[156:159], v[200:203], v[34:37]
	v_mfma_f32_16x16x32_bf16 v[18:21], v[152:155], v[204:207], v[18:21]
	v_mfma_f32_16x16x32_bf16 v[18:21], v[156:159], v[208:211], v[18:21]
	v_mfma_f32_16x16x32_bf16 v[46:49], v[160:163], v[176:179], v[46:49]
	v_mfma_f32_16x16x32_bf16 v[46:49], v[164:167], v[180:183], v[46:49]
	v_mfma_f32_16x16x32_bf16 v[30:33], v[160:163], v[184:187], v[30:33]
	v_mfma_f32_16x16x32_bf16 v[30:33], v[164:167], v[188:191], v[30:33]
	v_mfma_f32_16x16x32_bf16 v[14:17], v[160:163], v[192:195], v[14:17]
	v_mfma_f32_16x16x32_bf16 v[14:17], v[164:167], v[200:203], v[14:17]
	v_mfma_f32_16x16x32_bf16 v[6:9], v[160:163], v[204:207], v[6:9]
	v_mfma_f32_16x16x32_bf16 v[6:9], v[164:167], v[208:211], v[6:9]
	v_mfma_f32_16x16x32_bf16 v[42:45], v[168:171], v[176:179], v[42:45]
	v_mfma_f32_16x16x32_bf16 v[42:45], v[172:175], v[180:183], v[42:45]
	v_mfma_f32_16x16x32_bf16 v[26:29], v[168:171], v[184:187], v[26:29]
	v_mfma_f32_16x16x32_bf16 v[26:29], v[172:175], v[188:191], v[26:29]
	v_mfma_f32_16x16x32_bf16 v[10:13], v[168:171], v[192:195], v[10:13]
	v_mfma_f32_16x16x32_bf16 v[10:13], v[172:175], v[200:203], v[10:13]
	v_mfma_f32_16x16x32_bf16 v[2:5], v[168:171], v[204:207], v[2:5]
	v_mfma_f32_16x16x32_bf16 v[2:5], v[172:175], v[208:211], v[2:5]
	s_barrier
	s_add_i32 s53, s53, 2
	s_add_u32 s30, s30, 0x100
	s_addc_u32 s31, s31, 0
	s_add_u32 s51, s51, 0x100
	s_addc_u32 s52, s52, 0
	s_cmp_gt_u32 s53, 61
	s_cbranch_scc0 .LBB0_801
	s_and_b64 vcc, exec, s[20:21]
	s_cbranch_vccz .LBB0_804
	s_barrier
.LBB0_804:
	v_lshl_add_u32 v144, s48, 8, v140
	v_lshl_or_b32 v146, s47, 8, v142
	v_ashrrev_i32_e32 v145, 31, v144
	v_readlane_b32 s30, v251, 35
	v_ashrrev_i32_e32 v147, 31, v146
	v_lshlrev_b64 v[148:149], 13, v[144:145]
	v_readlane_b32 s31, v251, 36
	v_cvt_pk_bf16_f32 v110, v110, v111
	v_cvt_pk_bf16_f32 v111, v112, v113
	v_cvt_pk_bf16_f32 v112, v106, v107
	v_or_b32_e32 v106, 16, v144
	v_cvt_pk_bf16_f32 v94, v94, v95
	v_cvt_pk_bf16_f32 v95, v96, v97
	v_cvt_pk_bf16_f32 v96, v90, v91
	v_or_b32_e32 v90, 32, v144
	v_cvt_pk_bf16_f32 v78, v78, v79
	v_cvt_pk_bf16_f32 v79, v80, v81
	v_cvt_pk_bf16_f32 v80, v74, v75
	v_or_b32_e32 v74, 48, v144
	v_lshl_add_u64 v[148:149], s[30:31], 0, v[148:149]
	v_lshlrev_b64 v[146:147], 1, v[146:147]
	v_ashrrev_i32_e32 v107, 31, v106
	v_ashrrev_i32_e32 v91, 31, v90
	v_ashrrev_i32_e32 v75, 31, v74
	v_lshl_add_u64 v[148:149], v[148:149], 0, v[146:147]
	v_lshlrev_b64 v[106:107], 13, v[106:107]
	v_lshlrev_b64 v[90:91], 13, v[90:91]
	v_lshlrev_b64 v[74:75], 13, v[74:75]
	s_mov_b32 s23, 0x100000
	v_lshl_add_u64 v[106:107], s[30:31], 0, v[106:107]
	v_lshl_add_u64 v[90:91], s[30:31], 0, v[90:91]
	v_lshl_add_u64 v[74:75], s[30:31], 0, v[74:75]
	s_mov_b64 s[30:31], 0x100000
	v_cvt_pk_bf16_f32 v62, v62, v63
	v_cvt_pk_bf16_f32 v63, v64, v65
	v_cvt_pk_bf16_f32 v64, v58, v59
	v_add_co_u32_e32 v58, vcc, s23, v148
	v_cvt_pk_bf16_f32 v70, v70, v71
	v_cvt_pk_bf16_f32 v71, v72, v73
	v_cvt_pk_bf16_f32 v72, v66, v67
	v_lshl_add_u64 v[66:67], v[148:149], 0, s[30:31]
	v_addc_co_u32_e32 v59, vcc, 0, v149, vcc
	v_cvt_pk_bf16_f32 v46, v46, v47
	v_cvt_pk_bf16_f32 v47, v48, v49
	v_cvt_pk_bf16_f32 v48, v42, v43
	v_cvt_pk_bf16_f32 v49, v44, v45
	s_mov_b32 s23, 0x120000
	global_store_dwordx4 v[66:67], v[46:49], off offset:256
	s_mov_b64 s[30:31], 0x120000
	v_cvt_pk_bf16_f32 v30, v30, v31
	v_add_co_u32_e32 v48, vcc, s23, v148
	v_lshl_add_u64 v[46:47], v[148:149], 0, s[30:31]
	s_nop 0
	v_addc_co_u32_e32 v49, vcc, 0, v149, vcc
	v_cvt_pk_bf16_f32 v31, v32, v33
	v_cvt_pk_bf16_f32 v32, v26, v27
	v_cvt_pk_bf16_f32 v33, v28, v29
	s_mov_b32 s23, 0x140000
	global_store_dwordx4 v[46:47], v[30:33], off offset:256
	s_mov_b64 s[30:31], 0x140000
	v_cvt_pk_bf16_f32 v113, v108, v109
	v_add_co_u32_e32 v32, vcc, s23, v148
	v_lshl_add_u64 v[30:31], v[148:149], 0, s[30:31]
	s_nop 0
	v_addc_co_u32_e32 v33, vcc, 0, v149, vcc
	v_cvt_pk_bf16_f32 v14, v14, v15
	v_cvt_pk_bf16_f32 v15, v16, v17
	v_cvt_pk_bf16_f32 v16, v10, v11
	v_cvt_pk_bf16_f32 v17, v12, v13
	s_mov_b32 s23, 0x160000
	global_store_dwordx4 v[148:149], v[110:113], off offset:256
	v_cvt_pk_bf16_f32 v97, v92, v93
	global_store_dwordx4 v[30:31], v[14:17], off offset:256
	v_lshl_add_u64 v[110:111], v[106:107], 0, v[146:147]
	global_store_dwordx4 v[110:111], v[94:97], off offset:256
	v_add_co_u32_e32 v16, vcc, s23, v148
	s_nop 0
	v_lshl_add_u64 v[94:95], v[90:91], 0, v[146:147]
	v_cvt_pk_bf16_f32 v81, v76, v77
	s_mov_b64 s[30:31], 0x160000
	v_addc_co_u32_e32 v17, vcc, 0, v149, vcc
	v_cvt_pk_bf16_f32 v126, v126, v127
	v_cvt_pk_bf16_f32 v127, v128, v129
	v_cvt_pk_bf16_f32 v128, v122, v123
	v_cvt_pk_bf16_f32 v129, v124, v125
	v_cvt_pk_bf16_f32 v106, v118, v119
	v_cvt_pk_bf16_f32 v107, v120, v121
	v_cvt_pk_bf16_f32 v108, v114, v115
	v_cvt_pk_bf16_f32 v109, v116, v117
	v_cvt_pk_bf16_f32 v90, v102, v103
	v_cvt_pk_bf16_f32 v91, v104, v105
	v_cvt_pk_bf16_f32 v92, v98, v99
	v_cvt_pk_bf16_f32 v93, v100, v101
	global_store_dwordx4 v[94:95], v[78:81], off offset:256
	v_cvt_pk_bf16_f32 v76, v82, v83
	v_cvt_pk_bf16_f32 v77, v84, v85
	v_lshl_add_u64 v[78:79], v[74:75], 0, v[146:147]
	v_cvt_pk_bf16_f32 v74, v86, v87
	v_cvt_pk_bf16_f32 v75, v88, v89
	v_cvt_pk_bf16_f32 v73, v68, v69
	v_cvt_pk_bf16_f32 v65, v60, v61
	v_cvt_pk_bf16_f32 v42, v54, v55
	v_cvt_pk_bf16_f32 v43, v56, v57
	v_cvt_pk_bf16_f32 v44, v50, v51
	v_cvt_pk_bf16_f32 v45, v52, v53
	v_cvt_pk_bf16_f32 v26, v38, v39
	v_cvt_pk_bf16_f32 v27, v40, v41
	v_cvt_pk_bf16_f32 v28, v34, v35
	v_cvt_pk_bf16_f32 v29, v36, v37
	v_lshl_add_u64 v[14:15], v[148:149], 0, s[30:31]
	v_cvt_pk_bf16_f32 v10, v22, v23
	v_cvt_pk_bf16_f32 v11, v24, v25
	v_cvt_pk_bf16_f32 v12, v18, v19
	v_cvt_pk_bf16_f32 v13, v20, v21
	v_cvt_pk_bf16_f32 v6, v6, v7
	v_cvt_pk_bf16_f32 v7, v8, v9
	v_cvt_pk_bf16_f32 v8, v2, v3
	v_cvt_pk_bf16_f32 v9, v4, v5
	s_andn2_b64 vcc, exec, s[38:39]
	s_mov_b64 s[30:31], -1
	s_mov_b32 s54, 0x5c401000
	global_store_dwordx4 v[148:149], v[126:129], off
	global_store_dwordx4 v[110:111], v[106:109], off
	global_store_dwordx4 v[94:95], v[90:93], off
	global_store_dwordx4 v[78:79], v[74:77], off
	global_store_dwordx4 v[78:79], v[70:73], off offset:256
	global_store_dwordx4 v[58:59], v[62:65], off
	global_store_dwordx4 v[48:49], v[42:45], off
	global_store_dwordx4 v[32:33], v[26:29], off
	global_store_dwordx4 v[16:17], v[10:13], off
	global_store_dwordx4 v[14:15], v[6:9], off offset:256
	s_cbranch_vccnz .LBB0_793
	s_mov_b32 s100, 0
	s_andn2_b64 vcc, exec, s[0:1]
	s_cbranch_vccnz .LBB0_792
	s_mov_b32 s100, 1
	s_branch .LBB0_792
